# combo15 + back-edge rotation: K-loop counter / pointer updates moved from behind the last barrier into the tail of load segment 4 (only the exit compare and branch stay behind the barrier)
# baseline (speedup 1.0000x reference)
; #define PG8_STAGE(bufoff, gbase, unused) do { _Pragma("unroll") for (int _i = 0; _i < 2; ++_i) \
;         __builtin_amdgcn_global_load_lds((const unsigned*)((const char*)(gbase) + voff + _i * 8192), (LAS unsigned*)(lds + (bufoff) + ldsw + _i * 8192), 16, 0, 0); } while (0)
; #define PG8_LDA(dst, b, h) do { _Pragma("unroll") for (int m = 0; m < 4; ++m) _Pragma("unroll") for (int k = 0; k < 2; ++k) dst[m][k] = *(const LAS bf16x8*)(lds + PG8_SA(b, h) + aoff + m * 2048 + (FP8 ? k * 16 : k * 1024)); } while (0)
; #define PG8_LDB(dst, b, h) do { _Pragma("unroll") for (int n = 0; n < 2; ++n) _Pragma("unroll") for (int k = 0; k < 2; ++k) dst[n][k] = *(const LAS bf16x8*)(lds + PG8_SB(b, h) + boff + n * 2048 + (FP8 ? k * 16 : k * 1024)); } while (0)
; #define PG8_WAIT_V(n) asm volatile("s_waitcnt vmcnt(" #n ")" ::: "memory")
; #define PG8_WAIT_L(n) asm volatile("s_waitcnt lgkmcnt(" #n ")" ::: "memory")
; #define PG8_BAR __builtin_amdgcn_s_barrier()
; #define PG8_SCHED __builtin_amdgcn_sched_barrier(0)
; template <class Epi, class Sched, bool ALIGN_EPI, bool SP2, int MODE  >
; __device__ __forceinline__ void gemm_phase(LAS unsigned char* lds, const Gemm g, const Sched S, const Epi E, unsigned long long& probe_acc, int epi_id, int wv) {
;     ...
;         for (int t = 0; t < nt; t += 2) {
;             const bool last = (t == nt - 2);
;             const char* a1 = cA + (size_t)(t + 1) * kstep;
;             const char* a2 = last ? nA : cA + (size_t)(t + 2) * kstep; const char* b2 = last ? nB : cB + (size_t)(t + 2) * kstep;
;             const char* a3 = a2 + kstep; const char* b3 = b2 + kstep;
;             if constexpr (SP2) {
;             PG8_LDB(B0, 0, 0); PG8_LDB(B1, 0, 1); PG8_SCHED; PG8_LDA(At, 0, 0); PG8_STAGE(PG8_SA(1, 1), a1 + hA, voffA);
;             PG8_WAIT_V(8); PG8_WAIT_L(0); PG8_BAR; PG8_MMA(0, 0, At, B0); PG8_MMA(0, 1, At, B1); PG8_BAR; PG8_SCHED;
;             PG8_LDA(At, 0, 1); PG8_STAGE(PG8_SB(0, 0), b2, voffB); PG8_STAGE(PG8_SB(0, 1), b2 + hB, voffB); PG8_STAGE(PG8_SA(0, 0), a2, voffA);
;             PG8_WAIT_V(8); PG8_WAIT_L(0); PG8_BAR; PG8_MMA(1, 0, At, B0); PG8_MMA(1, 1, At, B1); PG8_BAR; PG8_SCHED;
.LBB0_326:
	v_add_u32_e32 v0, s39, v212
	ds_read_b128 v[132:135], v0
	ds_read_b128 v[136:139], v0 offset:1024
	ds_read_b128 v[140:143], v0 offset:2048
	ds_read_b128 v[144:147], v0 offset:3072
	v_add_u32_e32 v0, s65, v212
	ds_read_b128 v[148:151], v0
	ds_read_b128 v[152:155], v0 offset:1024
	ds_read_b128 v[156:159], v0 offset:2048
	ds_read_b128 v[160:163], v0 offset:3072
	s_add_u32 s30, s28, 0x8000
	s_addc_u32 s31, s29, 0
	s_cmp_eq_u32 s14, 12
	s_cselect_b32 s23, s27, s31
	s_cselect_b32 s22, s46, s30
	s_cselect_b32 s21, vcc_lo, s17
	s_cselect_b32 s20, vcc_hi, s16
	v_lshl_add_u64 v[184:185], s[28:29], 0, v[130:131]
	v_lshl_add_u64 v[204:205], v[184:185], 0, s[80:81]
	s_add_i32 m0, s85, 0xc000
	ds_read_b128 v[164:167], v213
	ds_read_b128 v[168:171], v213 offset:1024
	ds_read_b128 v[172:175], v213 offset:2048
	ds_read_b128 v[176:179], v213 offset:3072
	ds_read_b128 v[180:183], v213 offset:4096
	ds_read_b128 v[190:193], v213 offset:5120
	ds_read_b128 v[196:199], v213 offset:6144
	ds_read_b128 v[200:203], v213 offset:7168
	global_load_lds_dwordx4 v[204:205], off
	v_lshl_add_u64 v[184:185], v[184:185], 0, s[82:83]
	s_add_i32 m0, s85, 0xe000
	s_nop 0
	global_load_lds_dwordx4 v[184:185], off
	s_waitcnt vmcnt(8)
	s_waitcnt lgkmcnt(0)
	s_setprio 1
	s_barrier
	v_mfma_i32_16x16x64_i8 v[126:129], v[132:135], v[164:167], v[126:129]
	v_mfma_i32_16x16x64_i8 v[102:105], v[140:143], v[164:167], v[102:105]
	v_mfma_i32_16x16x64_i8 v[122:125], v[132:135], v[172:175], v[122:125]
	v_mfma_i32_16x16x64_i8 v[94:97], v[140:143], v[172:175], v[94:97]
	v_mfma_i32_16x16x64_i8 v[118:121], v[132:135], v[180:183], v[118:121]
	v_mfma_i32_16x16x64_i8 v[46:49], v[140:143], v[180:183], v[46:49]
	v_mfma_i32_16x16x64_i8 v[110:113], v[132:135], v[196:199], v[110:113]
	v_mfma_i32_16x16x64_i8 v[38:41], v[140:143], v[196:199], v[38:41]
	v_mfma_i32_16x16x64_i8 v[126:129], v[136:139], v[168:171], v[126:129]
	v_mfma_i32_16x16x64_i8 v[102:105], v[144:147], v[168:171], v[102:105]
	v_mfma_i32_16x16x64_i8 v[122:125], v[136:139], v[176:179], v[122:125]
	v_mfma_i32_16x16x64_i8 v[94:97], v[144:147], v[176:179], v[94:97]
	v_mfma_i32_16x16x64_i8 v[118:121], v[136:139], v[190:193], v[118:121]
	v_mfma_i32_16x16x64_i8 v[46:49], v[144:147], v[190:193], v[46:49]
	v_mfma_i32_16x16x64_i8 v[110:113], v[136:139], v[200:203], v[110:113]
	v_mfma_i32_16x16x64_i8 v[38:41], v[144:147], v[200:203], v[38:41]
	v_mfma_i32_16x16x64_i8 v[114:117], v[148:151], v[164:167], v[114:117]
	v_mfma_i32_16x16x64_i8 v[82:85], v[156:159], v[164:167], v[82:85]
	v_mfma_i32_16x16x64_i8 v[106:109], v[148:151], v[172:175], v[106:109]
	v_mfma_i32_16x16x64_i8 v[74:77], v[156:159], v[172:175], v[74:77]
	v_mfma_i32_16x16x64_i8 v[98:101], v[148:151], v[180:183], v[98:101]
	v_mfma_i32_16x16x64_i8 v[42:45], v[156:159], v[180:183], v[42:45]
	v_mfma_i32_16x16x64_i8 v[90:93], v[148:151], v[196:199], v[90:93]
	v_mfma_i32_16x16x64_i8 v[34:37], v[156:159], v[196:199], v[34:37]
	v_mfma_i32_16x16x64_i8 v[114:117], v[152:155], v[168:171], v[114:117]
	v_mfma_i32_16x16x64_i8 v[82:85], v[160:163], v[168:171], v[82:85]
	v_mfma_i32_16x16x64_i8 v[106:109], v[152:155], v[176:179], v[106:109]
	v_mfma_i32_16x16x64_i8 v[74:77], v[160:163], v[176:179], v[74:77]
	v_mfma_i32_16x16x64_i8 v[98:101], v[152:155], v[190:193], v[98:101]
	v_mfma_i32_16x16x64_i8 v[42:45], v[160:163], v[190:193], v[42:45]
	v_mfma_i32_16x16x64_i8 v[90:93], v[152:155], v[200:203], v[90:93]
	v_mfma_i32_16x16x64_i8 v[34:37], v[160:163], v[200:203], v[34:37]
	s_barrier
	s_setprio 0
	s_mov_b32 m0, s41
	v_lshl_add_u64 v[184:185], s[20:21], 0, v[130:131]
	ds_read_b128 v[164:167], v213 offset:16384
	ds_read_b128 v[168:171], v213 offset:17408
	ds_read_b128 v[172:175], v213 offset:18432
	ds_read_b128 v[176:179], v213 offset:19456
	ds_read_b128 v[180:183], v213 offset:20480
	ds_read_b128 v[190:193], v213 offset:21504
	ds_read_b128 v[196:199], v213 offset:22528
	ds_read_b128 v[200:203], v213 offset:23552
	global_load_lds_dwordx4 v[184:185], off
	v_lshl_add_u64 v[204:205], v[184:185], 0, s[70:71]
	s_mov_b32 m0, s64
	s_nop 0
	global_load_lds_dwordx4 v[204:205], off
	v_lshl_add_u64 v[204:205], v[184:185], 0, s[72:73]
	s_mov_b32 m0, s68
	s_nop 0
	global_load_lds_dwordx4 v[204:205], off
	v_lshl_add_u64 v[204:205], v[184:185], 0, s[74:75]
	s_mov_b32 m0, s84
	s_nop 0
	global_load_lds_dwordx4 v[204:205], off
	v_lshl_add_u64 v[204:205], s[22:23], 0, v[130:131]
	s_mov_b32 m0, s85
	v_lshl_add_u64 v[206:207], v[204:205], 0, s[70:71]
	global_load_lds_dwordx4 v[204:205], off
	s_mov_b32 m0, s86
	s_nop 0
	global_load_lds_dwordx4 v[206:207], off
	s_waitcnt vmcnt(8)
	s_waitcnt lgkmcnt(0)
	s_setprio 1
	s_barrier
; #define PG8_STAGE(bufoff, gbase, unused) do { _Pragma("unroll") for (int _i = 0; _i < 2; ++_i) \
;         __builtin_amdgcn_global_load_lds((const unsigned*)((const char*)(gbase) + voff + _i * 8192), (LAS unsigned*)(lds + (bufoff) + ldsw + _i * 8192), 16, 0, 0); } while (0)
; #define PG8_LDA(dst, b, h) do { _Pragma("unroll") for (int m = 0; m < 4; ++m) _Pragma("unroll") for (int k = 0; k < 2; ++k) dst[m][k] = *(const LAS bf16x8*)(lds + PG8_SA(b, h) + aoff + m * 2048 + (FP8 ? k * 16 : k * 1024)); } while (0)
; #define PG8_LDB(dst, b, h) do { _Pragma("unroll") for (int n = 0; n < 2; ++n) _Pragma("unroll") for (int k = 0; k < 2; ++k) dst[n][k] = *(const LAS bf16x8*)(lds + PG8_SB(b, h) + boff + n * 2048 + (FP8 ? k * 16 : k * 1024)); } while (0)
; #define PG8_WAIT_V(n) asm volatile("s_waitcnt vmcnt(" #n ")" ::: "memory")
; #define PG8_WAIT_L(n) asm volatile("s_waitcnt lgkmcnt(" #n ")" ::: "memory")
; #define PG8_BAR __builtin_amdgcn_s_barrier()
; #define PG8_SCHED __builtin_amdgcn_sched_barrier(0)
; template <class Epi, class Sched, bool ALIGN_EPI, bool SP2, int MODE  >
; __device__ __forceinline__ void gemm_phase(LAS unsigned char* lds, const Gemm g, const Sched S, const Epi E, unsigned long long& probe_acc, int epi_id, int wv) {
;     ...
;             PG8_WAIT_V(8); PG8_WAIT_L(0); PG8_BAR; PG8_MMA(1, 0, At, B0); PG8_MMA(1, 1, At, B1); PG8_BAR; PG8_SCHED;
;             PG8_LDB(B0, 1, 0); PG8_LDB(B1, 1, 1); PG8_SCHED; PG8_LDA(At, 1, 0); PG8_STAGE(PG8_SA(0, 1), a2 + hA, voffA);
;             PG8_WAIT_V(8); PG8_WAIT_L(0); PG8_BAR; PG8_MMA(0, 0, At, B0); PG8_MMA(0, 1, At, B1); PG8_BAR; PG8_SCHED;
	v_mfma_i32_16x16x64_i8 v[86:89], v[132:135], v[164:167], v[86:89]
	v_mfma_i32_16x16x64_i8 v[30:33], v[140:143], v[164:167], v[30:33]
	v_mfma_i32_16x16x64_i8 v[78:81], v[132:135], v[172:175], v[78:81]
	v_mfma_i32_16x16x64_i8 v[22:25], v[140:143], v[172:175], v[22:25]
	v_mfma_i32_16x16x64_i8 v[70:73], v[132:135], v[180:183], v[70:73]
	v_mfma_i32_16x16x64_i8 v[14:17], v[140:143], v[180:183], v[14:17]
	v_mfma_i32_16x16x64_i8 v[62:65], v[132:135], v[196:199], v[62:65]
	v_mfma_i32_16x16x64_i8 v[2:5], v[140:143], v[196:199], v[2:5]
	v_mfma_i32_16x16x64_i8 v[86:89], v[136:139], v[168:171], v[86:89]
	v_mfma_i32_16x16x64_i8 v[30:33], v[144:147], v[168:171], v[30:33]
	v_mfma_i32_16x16x64_i8 v[78:81], v[136:139], v[176:179], v[78:81]
	v_mfma_i32_16x16x64_i8 v[22:25], v[144:147], v[176:179], v[22:25]
	v_mfma_i32_16x16x64_i8 v[70:73], v[136:139], v[190:193], v[70:73]
	v_mfma_i32_16x16x64_i8 v[14:17], v[144:147], v[190:193], v[14:17]
	v_mfma_i32_16x16x64_i8 v[62:65], v[136:139], v[200:203], v[62:65]
	v_mfma_i32_16x16x64_i8 v[2:5], v[144:147], v[200:203], v[2:5]
	v_mfma_i32_16x16x64_i8 v[66:69], v[148:151], v[164:167], v[66:69]
	v_mfma_i32_16x16x64_i8 v[26:29], v[156:159], v[164:167], v[26:29]
	v_mfma_i32_16x16x64_i8 v[58:61], v[148:151], v[172:175], v[58:61]
	v_mfma_i32_16x16x64_i8 v[18:21], v[156:159], v[172:175], v[18:21]
	v_mfma_i32_16x16x64_i8 v[54:57], v[148:151], v[180:183], v[54:57]
	v_mfma_i32_16x16x64_i8 v[10:13], v[156:159], v[180:183], v[10:13]
	v_mfma_i32_16x16x64_i8 v[50:53], v[148:151], v[196:199], v[50:53]
	v_mfma_i32_16x16x64_i8 v[6:9], v[156:159], v[196:199], v[6:9]
	v_mfma_i32_16x16x64_i8 v[66:69], v[152:155], v[168:171], v[66:69]
	v_mfma_i32_16x16x64_i8 v[26:29], v[160:163], v[168:171], v[26:29]
	v_mfma_i32_16x16x64_i8 v[58:61], v[152:155], v[176:179], v[58:61]
	v_mfma_i32_16x16x64_i8 v[18:21], v[160:163], v[176:179], v[18:21]
	v_mfma_i32_16x16x64_i8 v[54:57], v[152:155], v[190:193], v[54:57]
	v_mfma_i32_16x16x64_i8 v[10:13], v[160:163], v[190:193], v[10:13]
	v_mfma_i32_16x16x64_i8 v[50:53], v[152:155], v[200:203], v[50:53]
	v_mfma_i32_16x16x64_i8 v[6:9], v[160:163], v[200:203], v[6:9]
	s_barrier
	s_setprio 0
	v_add_u32_e32 v0, s90, v212
	ds_read_b128 v[132:135], v0
	ds_read_b128 v[136:139], v0 offset:1024
	ds_read_b128 v[140:143], v0 offset:2048
	ds_read_b128 v[144:147], v0 offset:3072
	v_add_u32_e32 v0, s95, v212
	ds_read_b128 v[148:151], v0
	ds_read_b128 v[152:155], v0 offset:1024
	ds_read_b128 v[156:159], v0 offset:2048
	ds_read_b128 v[160:163], v0 offset:3072
	s_mov_b32 m0, s87
	v_lshl_add_u64 v[206:207], v[204:205], 0, s[72:73]
	ds_read_b128 v[164:167], v213 offset:32768
	ds_read_b128 v[168:171], v213 offset:33792
	ds_read_b128 v[172:175], v213 offset:34816
	ds_read_b128 v[176:179], v213 offset:35840
	ds_read_b128 v[180:183], v213 offset:36864
	ds_read_b128 v[190:193], v213 offset:37888
	ds_read_b128 v[196:199], v213 offset:38912
	ds_read_b128 v[200:203], v213 offset:39936
	global_load_lds_dwordx4 v[206:207], off
	v_lshl_add_u64 v[206:207], v[204:205], 0, s[74:75]
	s_mov_b32 m0, s88
	s_nop 0
	global_load_lds_dwordx4 v[206:207], off
	s_waitcnt vmcnt(8)
	s_waitcnt lgkmcnt(0)
	s_setprio 1
	s_barrier
	v_mfma_i32_16x16x64_i8 v[126:129], v[132:135], v[164:167], v[126:129]
	v_mfma_i32_16x16x64_i8 v[102:105], v[140:143], v[164:167], v[102:105]
	v_mfma_i32_16x16x64_i8 v[122:125], v[132:135], v[172:175], v[122:125]
	v_mfma_i32_16x16x64_i8 v[94:97], v[140:143], v[172:175], v[94:97]
	v_mfma_i32_16x16x64_i8 v[118:121], v[132:135], v[180:183], v[118:121]
	v_mfma_i32_16x16x64_i8 v[46:49], v[140:143], v[180:183], v[46:49]
	v_mfma_i32_16x16x64_i8 v[110:113], v[132:135], v[196:199], v[110:113]
	v_mfma_i32_16x16x64_i8 v[38:41], v[140:143], v[196:199], v[38:41]
	v_mfma_i32_16x16x64_i8 v[126:129], v[136:139], v[168:171], v[126:129]
	v_mfma_i32_16x16x64_i8 v[102:105], v[144:147], v[168:171], v[102:105]
	v_mfma_i32_16x16x64_i8 v[122:125], v[136:139], v[176:179], v[122:125]
	v_mfma_i32_16x16x64_i8 v[94:97], v[144:147], v[176:179], v[94:97]
	v_mfma_i32_16x16x64_i8 v[118:121], v[136:139], v[190:193], v[118:121]
	v_mfma_i32_16x16x64_i8 v[46:49], v[144:147], v[190:193], v[46:49]
	v_mfma_i32_16x16x64_i8 v[110:113], v[136:139], v[200:203], v[110:113]
	v_mfma_i32_16x16x64_i8 v[38:41], v[144:147], v[200:203], v[38:41]
	v_mfma_i32_16x16x64_i8 v[114:117], v[148:151], v[164:167], v[114:117]
	v_mfma_i32_16x16x64_i8 v[82:85], v[156:159], v[164:167], v[82:85]
	v_mfma_i32_16x16x64_i8 v[106:109], v[148:151], v[172:175], v[106:109]
	v_mfma_i32_16x16x64_i8 v[74:77], v[156:159], v[172:175], v[74:77]
	v_mfma_i32_16x16x64_i8 v[98:101], v[148:151], v[180:183], v[98:101]
	v_mfma_i32_16x16x64_i8 v[42:45], v[156:159], v[180:183], v[42:45]
	v_mfma_i32_16x16x64_i8 v[90:93], v[148:151], v[196:199], v[90:93]
	v_mfma_i32_16x16x64_i8 v[34:37], v[156:159], v[196:199], v[34:37]
	v_mfma_i32_16x16x64_i8 v[114:117], v[152:155], v[168:171], v[114:117]
	v_mfma_i32_16x16x64_i8 v[82:85], v[160:163], v[168:171], v[82:85]
	v_mfma_i32_16x16x64_i8 v[106:109], v[152:155], v[176:179], v[106:109]
	v_mfma_i32_16x16x64_i8 v[74:77], v[160:163], v[176:179], v[74:77]
	v_mfma_i32_16x16x64_i8 v[98:101], v[152:155], v[190:193], v[98:101]
	v_mfma_i32_16x16x64_i8 v[42:45], v[160:163], v[190:193], v[42:45]
	v_mfma_i32_16x16x64_i8 v[90:93], v[152:155], v[200:203], v[90:93]
	v_mfma_i32_16x16x64_i8 v[34:37], v[160:163], v[200:203], v[34:37]
	s_barrier
; #define PG8_STAGE(bufoff, gbase, unused) do { _Pragma("unroll") for (int _i = 0; _i < 2; ++_i) \
;         __builtin_amdgcn_global_load_lds((const unsigned*)((const char*)(gbase) + voff + _i * 8192), (LAS unsigned*)(lds + (bufoff) + ldsw + _i * 8192), 16, 0, 0); } while (0)
; #define PG8_LDA(dst, b, h) do { _Pragma("unroll") for (int m = 0; m < 4; ++m) _Pragma("unroll") for (int k = 0; k < 2; ++k) dst[m][k] = *(const LAS bf16x8*)(lds + PG8_SA(b, h) + aoff + m * 2048 + (FP8 ? k * 16 : k * 1024)); } while (0)
; #define PG8_WAIT_V(n) asm volatile("s_waitcnt vmcnt(" #n ")" ::: "memory")
; #define PG8_WAIT_L(n) asm volatile("s_waitcnt lgkmcnt(" #n ")" ::: "memory")
; #define PG8_BAR __builtin_amdgcn_s_barrier()
; #define PG8_SCHED __builtin_amdgcn_sched_barrier(0)
; template <class Epi, class Sched, bool ALIGN_EPI, bool SP2, int MODE  >
; __device__ __forceinline__ void gemm_phase(LAS unsigned char* lds, const Gemm g, const Sched S, const Epi E, unsigned long long& probe_acc, int epi_id, int wv) {
;     ...
;         for (int t = 0; t < nt; t += 2) {
;             const bool last = (t == nt - 2);
;     ...
;             PG8_LDA(At, 1, 1); PG8_STAGE(PG8_SB(1, 0), b3, voffB); PG8_STAGE(PG8_SB(1, 1), b3 + hB, voffB); PG8_STAGE(PG8_SA(1, 0), a3, voffA);
;             PG8_WAIT_V(8); PG8_WAIT_L(0); PG8_BAR; PG8_MMA(1, 0, At, B0); PG8_MMA(1, 1, At, B1); PG8_BAR; PG8_SCHED;
	s_setprio 0
	s_mov_b32 m0, s91
	v_lshl_add_u64 v[206:207], v[184:185], 0, s[76:77]
	ds_read_b128 v[164:167], v213 offset:49152
	ds_read_b128 v[168:171], v213 offset:50176
	ds_read_b128 v[172:175], v213 offset:51200
	ds_read_b128 v[176:179], v213 offset:52224
	ds_read_b128 v[180:183], v213 offset:53248
	ds_read_b128 v[190:193], v213 offset:54272
	ds_read_b128 v[196:199], v213 offset:55296
	ds_read_b128 v[200:203], v213 offset:56320
	global_load_lds_dwordx4 v[206:207], off
	v_lshl_add_u64 v[206:207], v[184:185], 0, s[78:79]
	s_mov_b32 m0, s92
	s_nop 0
	global_load_lds_dwordx4 v[206:207], off
	v_lshl_add_u64 v[206:207], v[184:185], 0, s[80:81]
	s_mov_b32 m0, s2
	v_lshl_add_u64 v[184:185], v[184:185], 0, s[82:83]
	global_load_lds_dwordx4 v[206:207], off
	s_mov_b32 m0, s3
	s_nop 0
	global_load_lds_dwordx4 v[184:185], off
	v_lshl_add_u64 v[184:185], v[204:205], 0, s[76:77]
	s_mov_b32 m0, s93
	s_nop 0
	global_load_lds_dwordx4 v[184:185], off
	v_lshl_add_u64 v[184:185], v[204:205], 0, s[78:79]
	s_mov_b32 m0, s94
	s_nop 0
	global_load_lds_dwordx4 v[184:185], off
	s_add_i32 s14, s14, 2
	s_add_u32 s16, s16, 0x8000
	s_addc_u32 s17, s17, 0
	s_mov_b64 s[28:29], s[30:31]
	s_waitcnt vmcnt(8)
	s_waitcnt lgkmcnt(0)
	s_setprio 1
	s_barrier
	v_mfma_i32_16x16x64_i8 v[86:89], v[132:135], v[164:167], v[86:89]
	v_mfma_i32_16x16x64_i8 v[30:33], v[140:143], v[164:167], v[30:33]
	v_mfma_i32_16x16x64_i8 v[78:81], v[132:135], v[172:175], v[78:81]
	v_mfma_i32_16x16x64_i8 v[22:25], v[140:143], v[172:175], v[22:25]
	v_mfma_i32_16x16x64_i8 v[70:73], v[132:135], v[180:183], v[70:73]
	v_mfma_i32_16x16x64_i8 v[14:17], v[140:143], v[180:183], v[14:17]
	v_mfma_i32_16x16x64_i8 v[62:65], v[132:135], v[196:199], v[62:65]
	v_mfma_i32_16x16x64_i8 v[2:5], v[140:143], v[196:199], v[2:5]
	v_mfma_i32_16x16x64_i8 v[86:89], v[136:139], v[168:171], v[86:89]
	v_mfma_i32_16x16x64_i8 v[30:33], v[144:147], v[168:171], v[30:33]
	v_mfma_i32_16x16x64_i8 v[78:81], v[136:139], v[176:179], v[78:81]
	v_mfma_i32_16x16x64_i8 v[22:25], v[144:147], v[176:179], v[22:25]
	v_mfma_i32_16x16x64_i8 v[70:73], v[136:139], v[190:193], v[70:73]
	v_mfma_i32_16x16x64_i8 v[14:17], v[144:147], v[190:193], v[14:17]
	v_mfma_i32_16x16x64_i8 v[62:65], v[136:139], v[200:203], v[62:65]
	v_mfma_i32_16x16x64_i8 v[2:5], v[144:147], v[200:203], v[2:5]
	v_mfma_i32_16x16x64_i8 v[66:69], v[148:151], v[164:167], v[66:69]
	v_mfma_i32_16x16x64_i8 v[26:29], v[156:159], v[164:167], v[26:29]
	v_mfma_i32_16x16x64_i8 v[58:61], v[148:151], v[172:175], v[58:61]
	v_mfma_i32_16x16x64_i8 v[18:21], v[156:159], v[172:175], v[18:21]
	v_mfma_i32_16x16x64_i8 v[54:57], v[148:151], v[180:183], v[54:57]
	v_mfma_i32_16x16x64_i8 v[10:13], v[156:159], v[180:183], v[10:13]
	v_mfma_i32_16x16x64_i8 v[50:53], v[148:151], v[196:199], v[50:53]
	v_mfma_i32_16x16x64_i8 v[6:9], v[156:159], v[196:199], v[6:9]
	v_mfma_i32_16x16x64_i8 v[66:69], v[152:155], v[168:171], v[66:69]
	v_mfma_i32_16x16x64_i8 v[26:29], v[160:163], v[168:171], v[26:29]
	v_mfma_i32_16x16x64_i8 v[58:61], v[152:155], v[176:179], v[58:61]
	v_mfma_i32_16x16x64_i8 v[18:21], v[160:163], v[176:179], v[18:21]
	v_mfma_i32_16x16x64_i8 v[54:57], v[152:155], v[190:193], v[54:57]
	v_mfma_i32_16x16x64_i8 v[10:13], v[160:163], v[190:193], v[10:13]
	v_mfma_i32_16x16x64_i8 v[50:53], v[152:155], v[200:203], v[50:53]
	v_mfma_i32_16x16x64_i8 v[6:9], v[160:163], v[200:203], v[6:9]
	s_barrier
	s_setprio 0
	s_cmp_gt_u32 s14, 13
	s_cbranch_scc0 .LBB0_326
	v_readlane_b32 s14, v255, 11
	v_readlane_b32 s15, v255, 12
	s_and_b64 vcc, exec, s[14:15]
	s_cbranch_vccz .LBB0_329
	s_barrier

; #define PG8_STAGE(bufoff, gbase, unused) do { _Pragma("unroll") for (int _i = 0; _i < 2; ++_i) \
;         __builtin_amdgcn_global_load_lds((const unsigned*)((const char*)(gbase) + voff + _i * 8192), (LAS unsigned*)(lds + (bufoff) + ldsw + _i * 8192), 16, 0, 0); } while (0)
; #define PG8_LDA(dst, b, h) do { _Pragma("unroll") for (int m = 0; m < 4; ++m) _Pragma("unroll") for (int k = 0; k < 2; ++k) dst[m][k] = *(const LAS bf16x8*)(lds + PG8_SA(b, h) + aoff + m * 2048 + (FP8 ? k * 16 : k * 1024)); } while (0)
; #define PG8_LDB(dst, b, h) do { _Pragma("unroll") for (int n = 0; n < 2; ++n) _Pragma("unroll") for (int k = 0; k < 2; ++k) dst[n][k] = *(const LAS bf16x8*)(lds + PG8_SB(b, h) + boff + n * 2048 + (FP8 ? k * 16 : k * 1024)); } while (0)
; #define PG8_WAIT_V(n) asm volatile("s_waitcnt vmcnt(" #n ")" ::: "memory")
; #define PG8_WAIT_L(n) asm volatile("s_waitcnt lgkmcnt(" #n ")" ::: "memory")
; #define PG8_BAR __builtin_amdgcn_s_barrier()
; #define PG8_SCHED __builtin_amdgcn_sched_barrier(0)
; template <class Epi, class Sched, bool ALIGN_EPI, bool SP2, int MODE  >
; __device__ __forceinline__ void gemm_phase(LAS unsigned char* lds, const Gemm g, const Sched S, const Epi E, unsigned long long& probe_acc, int epi_id, int wv) {
;     ...
;         for (int t = 0; t < nt; t += 2) {
;             const bool last = (t == nt - 2);
;             const char* a1 = cA + (size_t)(t + 1) * kstep;
;             const char* a2 = last ? nA : cA + (size_t)(t + 2) * kstep; const char* b2 = last ? nB : cB + (size_t)(t + 2) * kstep;
;             const char* a3 = a2 + kstep; const char* b3 = b2 + kstep;
;             if constexpr (SP2) {
;             PG8_LDB(B0, 0, 0); PG8_LDB(B1, 0, 1); PG8_SCHED; PG8_LDA(At, 0, 0); PG8_STAGE(PG8_SA(1, 1), a1 + hA, voffA);
;             PG8_WAIT_V(8); PG8_WAIT_L(0); PG8_BAR; PG8_MMA(0, 0, At, B0); PG8_MMA(0, 1, At, B1); PG8_BAR; PG8_SCHED;
;             PG8_LDA(At, 0, 1); PG8_STAGE(PG8_SB(0, 0), b2, voffB); PG8_STAGE(PG8_SB(0, 1), b2 + hB, voffB); PG8_STAGE(PG8_SA(0, 0), a2, voffA);
;             PG8_WAIT_V(8); PG8_WAIT_L(0); PG8_BAR; PG8_MMA(1, 0, At, B0); PG8_MMA(1, 1, At, B1); PG8_BAR; PG8_SCHED;
.LBB0_365:
	v_add_u32_e32 v0, s2, v166
	s_waitcnt vmcnt(0)
	ds_read_b128 v[130:133], v0
	ds_read_b128 v[134:137], v0 offset:1024
	ds_read_b128 v[138:141], v0 offset:2048
	ds_read_b128 v[142:145], v0 offset:3072
	v_add_u32_e32 v0, s23, v166
	ds_read_b128 v[146:149], v0
	ds_read_b128 v[150:153], v0 offset:1024
	s_waitcnt lgkmcnt(0)
	ds_read_b128 v[156:159], v0 offset:2048
	ds_read_b128 v[160:163], v0 offset:3072
	s_add_u32 s20, s18, 0x8000
	s_addc_u32 s21, s19, 0
	s_cmp_eq_u32 s95, 28
	s_cselect_b32 vcc_hi, s46, s21
	s_cselect_b32 vcc_lo, s90, s20
	s_cselect_b32 s9, s91, s94
	s_cselect_b32 s8, s92, s93
	v_lshl_add_u64 v[184:185], s[18:19], 0, v[154:155]
	v_lshl_add_u64 v[204:205], v[184:185], 0, s[52:53]
	s_add_i32 m0, s26, 0xc000
	ds_read_b128 v[168:171], v167
	ds_read_b128 v[172:175], v167 offset:1024
	ds_read_b128 v[176:179], v167 offset:2048
	ds_read_b128 v[180:183], v167 offset:3072
	ds_read_b128 v[188:191], v167 offset:4096
	ds_read_b128 v[192:195], v167 offset:5120
	ds_read_b128 v[196:199], v167 offset:6144
	ds_read_b128 v[200:203], v167 offset:7168
	global_load_lds_dwordx4 v[204:205], off
	v_lshl_add_u64 v[184:185], v[184:185], 0, s[54:55]
	s_add_i32 m0, s26, 0xe000
	s_nop 0
	global_load_lds_dwordx4 v[184:185], off
	s_waitcnt vmcnt(8)
	s_waitcnt lgkmcnt(0)
	s_setprio 1
	s_barrier
	v_mfma_f32_16x16x32_bf16 v[126:129], v[130:133], v[168:171], v[126:129]
	v_mfma_f32_16x16x32_bf16 v[122:125], v[138:141], v[168:171], v[122:125]
	v_mfma_f32_16x16x32_bf16 v[110:113], v[130:133], v[176:179], v[110:113]
	v_mfma_f32_16x16x32_bf16 v[106:109], v[138:141], v[176:179], v[106:109]
	v_mfma_f32_16x16x32_bf16 v[94:97], v[130:133], v[188:191], v[94:97]
	v_mfma_f32_16x16x32_bf16 v[90:93], v[138:141], v[188:191], v[90:93]
	v_mfma_f32_16x16x32_bf16 v[78:81], v[130:133], v[196:199], v[78:81]
	v_mfma_f32_16x16x32_bf16 v[74:77], v[138:141], v[196:199], v[74:77]
	v_mfma_f32_16x16x32_bf16 v[126:129], v[134:137], v[172:175], v[126:129]
	v_mfma_f32_16x16x32_bf16 v[122:125], v[142:145], v[172:175], v[122:125]
	v_mfma_f32_16x16x32_bf16 v[110:113], v[134:137], v[180:183], v[110:113]
	v_mfma_f32_16x16x32_bf16 v[106:109], v[142:145], v[180:183], v[106:109]
	v_mfma_f32_16x16x32_bf16 v[94:97], v[134:137], v[192:195], v[94:97]
	v_mfma_f32_16x16x32_bf16 v[90:93], v[142:145], v[192:195], v[90:93]
	v_mfma_f32_16x16x32_bf16 v[78:81], v[134:137], v[200:203], v[78:81]
	v_mfma_f32_16x16x32_bf16 v[74:77], v[142:145], v[200:203], v[74:77]
	v_mfma_f32_16x16x32_bf16 v[118:121], v[146:149], v[168:171], v[118:121]
	v_mfma_f32_16x16x32_bf16 v[114:117], v[156:159], v[168:171], v[114:117]
	v_mfma_f32_16x16x32_bf16 v[102:105], v[146:149], v[176:179], v[102:105]
	v_mfma_f32_16x16x32_bf16 v[98:101], v[156:159], v[176:179], v[98:101]
	v_mfma_f32_16x16x32_bf16 v[86:89], v[146:149], v[188:191], v[86:89]
	v_mfma_f32_16x16x32_bf16 v[82:85], v[156:159], v[188:191], v[82:85]
	v_mfma_f32_16x16x32_bf16 v[70:73], v[146:149], v[196:199], v[70:73]
	v_mfma_f32_16x16x32_bf16 v[66:69], v[156:159], v[196:199], v[66:69]
	v_mfma_f32_16x16x32_bf16 v[118:121], v[150:153], v[172:175], v[118:121]
	v_mfma_f32_16x16x32_bf16 v[114:117], v[160:163], v[172:175], v[114:117]
	v_mfma_f32_16x16x32_bf16 v[102:105], v[150:153], v[180:183], v[102:105]
	v_mfma_f32_16x16x32_bf16 v[98:101], v[160:163], v[180:183], v[98:101]
	v_mfma_f32_16x16x32_bf16 v[86:89], v[150:153], v[192:195], v[86:89]
	v_mfma_f32_16x16x32_bf16 v[82:85], v[160:163], v[192:195], v[82:85]
	v_mfma_f32_16x16x32_bf16 v[70:73], v[150:153], v[200:203], v[70:73]
	v_mfma_f32_16x16x32_bf16 v[66:69], v[160:163], v[200:203], v[66:69]
	s_barrier
	s_setprio 0
	s_mov_b32 m0, s3
	v_lshl_add_u64 v[184:185], s[8:9], 0, v[154:155]
	ds_read_b128 v[168:171], v167 offset:16384
	ds_read_b128 v[172:175], v167 offset:17408
	ds_read_b128 v[176:179], v167 offset:18432
	ds_read_b128 v[180:183], v167 offset:19456
	ds_read_b128 v[188:191], v167 offset:20480
	ds_read_b128 v[192:195], v167 offset:21504
	ds_read_b128 v[196:199], v167 offset:22528
	ds_read_b128 v[200:203], v167 offset:23552
	global_load_lds_dwordx4 v[184:185], off
	v_lshl_add_u64 v[204:205], v[184:185], 0, s[70:71]
	s_mov_b32 m0, s22
	s_nop 0
	global_load_lds_dwordx4 v[204:205], off
	v_lshl_add_u64 v[204:205], v[184:185], 0, s[96:97]
	s_mov_b32 m0, s24
	s_nop 0
	global_load_lds_dwordx4 v[204:205], off
	v_lshl_add_u64 v[204:205], v[184:185], 0, s[60:61]
	s_mov_b32 m0, s25
	s_nop 0
	global_load_lds_dwordx4 v[204:205], off
	v_lshl_add_u64 v[204:205], vcc, 0, v[154:155]
	s_mov_b32 m0, s26
	v_lshl_add_u64 v[206:207], v[204:205], 0, s[70:71]
	global_load_lds_dwordx4 v[204:205], off
	s_mov_b32 m0, s27
	s_nop 0
	global_load_lds_dwordx4 v[206:207], off
	s_waitcnt vmcnt(8)
	s_waitcnt lgkmcnt(0)
	s_setprio 1
	s_barrier
; #define PG8_STAGE(bufoff, gbase, unused) do { _Pragma("unroll") for (int _i = 0; _i < 2; ++_i) \
;         __builtin_amdgcn_global_load_lds((const unsigned*)((const char*)(gbase) + voff + _i * 8192), (LAS unsigned*)(lds + (bufoff) + ldsw + _i * 8192), 16, 0, 0); } while (0)
; #define PG8_LDA(dst, b, h) do { _Pragma("unroll") for (int m = 0; m < 4; ++m) _Pragma("unroll") for (int k = 0; k < 2; ++k) dst[m][k] = *(const LAS bf16x8*)(lds + PG8_SA(b, h) + aoff + m * 2048 + (FP8 ? k * 16 : k * 1024)); } while (0)
; #define PG8_LDB(dst, b, h) do { _Pragma("unroll") for (int n = 0; n < 2; ++n) _Pragma("unroll") for (int k = 0; k < 2; ++k) dst[n][k] = *(const LAS bf16x8*)(lds + PG8_SB(b, h) + boff + n * 2048 + (FP8 ? k * 16 : k * 1024)); } while (0)
; #define PG8_WAIT_V(n) asm volatile("s_waitcnt vmcnt(" #n ")" ::: "memory")
; #define PG8_WAIT_L(n) asm volatile("s_waitcnt lgkmcnt(" #n ")" ::: "memory")
; #define PG8_BAR __builtin_amdgcn_s_barrier()
; #define PG8_SCHED __builtin_amdgcn_sched_barrier(0)
; template <class Epi, class Sched, bool ALIGN_EPI, bool SP2, int MODE  >
; __device__ __forceinline__ void gemm_phase(LAS unsigned char* lds, const Gemm g, const Sched S, const Epi E, unsigned long long& probe_acc, int epi_id, int wv) {
;     ...
;             PG8_WAIT_V(8); PG8_WAIT_L(0); PG8_BAR; PG8_MMA(1, 0, At, B0); PG8_MMA(1, 1, At, B1); PG8_BAR; PG8_SCHED;
;             PG8_LDB(B0, 1, 0); PG8_LDB(B1, 1, 1); PG8_SCHED; PG8_LDA(At, 1, 0); PG8_STAGE(PG8_SA(0, 1), a2 + hA, voffA);
;             PG8_WAIT_V(8); PG8_WAIT_L(0); PG8_BAR; PG8_MMA(0, 0, At, B0); PG8_MMA(0, 1, At, B1); PG8_BAR; PG8_SCHED;
	v_mfma_f32_16x16x32_bf16 v[62:65], v[130:133], v[168:171], v[62:65]
	v_mfma_f32_16x16x32_bf16 v[58:61], v[138:141], v[168:171], v[58:61]
	v_mfma_f32_16x16x32_bf16 v[46:49], v[130:133], v[176:179], v[46:49]
	v_mfma_f32_16x16x32_bf16 v[42:45], v[138:141], v[176:179], v[42:45]
	v_mfma_f32_16x16x32_bf16 v[30:33], v[130:133], v[188:191], v[30:33]
	v_mfma_f32_16x16x32_bf16 v[26:29], v[138:141], v[188:191], v[26:29]
	v_mfma_f32_16x16x32_bf16 v[14:17], v[130:133], v[196:199], v[14:17]
	v_mfma_f32_16x16x32_bf16 v[10:13], v[138:141], v[196:199], v[10:13]
	v_mfma_f32_16x16x32_bf16 v[62:65], v[134:137], v[172:175], v[62:65]
	v_mfma_f32_16x16x32_bf16 v[58:61], v[142:145], v[172:175], v[58:61]
	v_mfma_f32_16x16x32_bf16 v[46:49], v[134:137], v[180:183], v[46:49]
	v_mfma_f32_16x16x32_bf16 v[42:45], v[142:145], v[180:183], v[42:45]
	v_mfma_f32_16x16x32_bf16 v[30:33], v[134:137], v[192:195], v[30:33]
	v_mfma_f32_16x16x32_bf16 v[26:29], v[142:145], v[192:195], v[26:29]
	v_mfma_f32_16x16x32_bf16 v[14:17], v[134:137], v[200:203], v[14:17]
	v_mfma_f32_16x16x32_bf16 v[10:13], v[142:145], v[200:203], v[10:13]
	v_mfma_f32_16x16x32_bf16 v[54:57], v[146:149], v[168:171], v[54:57]
	v_mfma_f32_16x16x32_bf16 v[50:53], v[156:159], v[168:171], v[50:53]
	v_mfma_f32_16x16x32_bf16 v[38:41], v[146:149], v[176:179], v[38:41]
	v_mfma_f32_16x16x32_bf16 v[34:37], v[156:159], v[176:179], v[34:37]
	v_mfma_f32_16x16x32_bf16 v[22:25], v[146:149], v[188:191], v[22:25]
	v_mfma_f32_16x16x32_bf16 v[18:21], v[156:159], v[188:191], v[18:21]
	v_mfma_f32_16x16x32_bf16 v[6:9], v[146:149], v[196:199], v[6:9]
	v_mfma_f32_16x16x32_bf16 v[2:5], v[156:159], v[196:199], v[2:5]
	v_mfma_f32_16x16x32_bf16 v[54:57], v[150:153], v[172:175], v[54:57]
	v_mfma_f32_16x16x32_bf16 v[50:53], v[160:163], v[172:175], v[50:53]
	v_mfma_f32_16x16x32_bf16 v[38:41], v[150:153], v[180:183], v[38:41]
	v_mfma_f32_16x16x32_bf16 v[34:37], v[160:163], v[180:183], v[34:37]
	v_mfma_f32_16x16x32_bf16 v[22:25], v[150:153], v[192:195], v[22:25]
	v_mfma_f32_16x16x32_bf16 v[18:21], v[160:163], v[192:195], v[18:21]
	v_mfma_f32_16x16x32_bf16 v[6:9], v[150:153], v[200:203], v[6:9]
	v_mfma_f32_16x16x32_bf16 v[2:5], v[160:163], v[200:203], v[2:5]
	s_barrier
	s_setprio 0
	v_add_u32_e32 v0, s31, v166
	ds_read_b128 v[130:133], v0
	ds_read_b128 v[134:137], v0 offset:1024
	ds_read_b128 v[138:141], v0 offset:2048
	ds_read_b128 v[142:145], v0 offset:3072
	v_add_u32_e32 v0, s39, v166
	ds_read_b128 v[146:149], v0
	ds_read_b128 v[150:153], v0 offset:1024
	ds_read_b128 v[156:159], v0 offset:2048
	ds_read_b128 v[160:163], v0 offset:3072
	s_mov_b32 m0, s28
	v_lshl_add_u64 v[206:207], v[204:205], 0, s[96:97]
	ds_read_b128 v[168:171], v167 offset:32768
	ds_read_b128 v[172:175], v167 offset:33792
	ds_read_b128 v[176:179], v167 offset:34816
	ds_read_b128 v[180:183], v167 offset:35840
	ds_read_b128 v[188:191], v167 offset:36864
	ds_read_b128 v[192:195], v167 offset:37888
	ds_read_b128 v[196:199], v167 offset:38912
	ds_read_b128 v[200:203], v167 offset:39936
	global_load_lds_dwordx4 v[206:207], off
	v_lshl_add_u64 v[206:207], v[204:205], 0, s[60:61]
	s_mov_b32 m0, s29
	s_nop 0
	global_load_lds_dwordx4 v[206:207], off
	s_waitcnt vmcnt(8)
	s_waitcnt lgkmcnt(0)
	s_setprio 1
	s_barrier
	v_mfma_f32_16x16x32_bf16 v[126:129], v[130:133], v[168:171], v[126:129]
	v_mfma_f32_16x16x32_bf16 v[122:125], v[138:141], v[168:171], v[122:125]
	v_mfma_f32_16x16x32_bf16 v[110:113], v[130:133], v[176:179], v[110:113]
	v_mfma_f32_16x16x32_bf16 v[106:109], v[138:141], v[176:179], v[106:109]
	v_mfma_f32_16x16x32_bf16 v[94:97], v[130:133], v[188:191], v[94:97]
	v_mfma_f32_16x16x32_bf16 v[90:93], v[138:141], v[188:191], v[90:93]
	v_mfma_f32_16x16x32_bf16 v[78:81], v[130:133], v[196:199], v[78:81]
	v_mfma_f32_16x16x32_bf16 v[74:77], v[138:141], v[196:199], v[74:77]
	v_mfma_f32_16x16x32_bf16 v[126:129], v[134:137], v[172:175], v[126:129]
	v_mfma_f32_16x16x32_bf16 v[122:125], v[142:145], v[172:175], v[122:125]
	v_mfma_f32_16x16x32_bf16 v[110:113], v[134:137], v[180:183], v[110:113]
	v_mfma_f32_16x16x32_bf16 v[106:109], v[142:145], v[180:183], v[106:109]
	v_mfma_f32_16x16x32_bf16 v[94:97], v[134:137], v[192:195], v[94:97]
	v_mfma_f32_16x16x32_bf16 v[90:93], v[142:145], v[192:195], v[90:93]
	v_mfma_f32_16x16x32_bf16 v[78:81], v[134:137], v[200:203], v[78:81]
	v_mfma_f32_16x16x32_bf16 v[74:77], v[142:145], v[200:203], v[74:77]
	v_mfma_f32_16x16x32_bf16 v[118:121], v[146:149], v[168:171], v[118:121]
	v_mfma_f32_16x16x32_bf16 v[114:117], v[156:159], v[168:171], v[114:117]
	v_mfma_f32_16x16x32_bf16 v[102:105], v[146:149], v[176:179], v[102:105]
	v_mfma_f32_16x16x32_bf16 v[98:101], v[156:159], v[176:179], v[98:101]
	v_mfma_f32_16x16x32_bf16 v[86:89], v[146:149], v[188:191], v[86:89]
	v_mfma_f32_16x16x32_bf16 v[82:85], v[156:159], v[188:191], v[82:85]
	v_mfma_f32_16x16x32_bf16 v[70:73], v[146:149], v[196:199], v[70:73]
	v_mfma_f32_16x16x32_bf16 v[66:69], v[156:159], v[196:199], v[66:69]
	v_mfma_f32_16x16x32_bf16 v[118:121], v[150:153], v[172:175], v[118:121]
	v_mfma_f32_16x16x32_bf16 v[114:117], v[160:163], v[172:175], v[114:117]
	v_mfma_f32_16x16x32_bf16 v[102:105], v[150:153], v[180:183], v[102:105]
	v_mfma_f32_16x16x32_bf16 v[98:101], v[160:163], v[180:183], v[98:101]
	v_mfma_f32_16x16x32_bf16 v[86:89], v[150:153], v[192:195], v[86:89]
	v_mfma_f32_16x16x32_bf16 v[82:85], v[160:163], v[192:195], v[82:85]
	v_mfma_f32_16x16x32_bf16 v[70:73], v[150:153], v[200:203], v[70:73]
	v_mfma_f32_16x16x32_bf16 v[66:69], v[160:163], v[200:203], v[66:69]
	s_barrier
; #define PG8_STAGE(bufoff, gbase, unused) do { _Pragma("unroll") for (int _i = 0; _i < 2; ++_i) \
;         __builtin_amdgcn_global_load_lds((const unsigned*)((const char*)(gbase) + voff + _i * 8192), (LAS unsigned*)(lds + (bufoff) + ldsw + _i * 8192), 16, 0, 0); } while (0)
; #define PG8_LDA(dst, b, h) do { _Pragma("unroll") for (int m = 0; m < 4; ++m) _Pragma("unroll") for (int k = 0; k < 2; ++k) dst[m][k] = *(const LAS bf16x8*)(lds + PG8_SA(b, h) + aoff + m * 2048 + (FP8 ? k * 16 : k * 1024)); } while (0)
; #define PG8_LDB(dst, b, h) do { _Pragma("unroll") for (int n = 0; n < 2; ++n) _Pragma("unroll") for (int k = 0; k < 2; ++k) dst[n][k] = *(const LAS bf16x8*)(lds + PG8_SB(b, h) + boff + n * 2048 + (FP8 ? k * 16 : k * 1024)); } while (0)
; template <class Epi, class Sched, bool ALIGN_EPI, bool SP2, int MODE  >
; __device__ __forceinline__ void gemm_phase(LAS unsigned char* lds, const Gemm g, const Sched S, const Epi E, unsigned long long& probe_acc, int epi_id, int wv) {
;     ...
;         for (int t = 0; t < nt; t += 2) {
;             const bool last = (t == nt - 2);
;             const char* a1 = cA + (size_t)(t + 1) * kstep;
;             const char* a2 = last ? nA : cA + (size_t)(t + 2) * kstep; const char* b2 = last ? nB : cB + (size_t)(t + 2) * kstep;
;             const char* a3 = a2 + kstep; const char* b3 = b2 + kstep;
;             if constexpr (SP2) {
;             PG8_LDB(B0, 0, 0); PG8_LDB(B1, 0, 1); PG8_SCHED; PG8_LDA(At, 0, 0); PG8_STAGE(PG8_SA(1, 1), a1 + hA, voffA);
;             PG8_WAIT_V(8); PG8_WAIT_L(0); PG8_BAR; PG8_MMA(0, 0, At, B0); PG8_MMA(0, 1, At, B1); PG8_BAR; PG8_SCHED;
;             PG8_LDA(At, 0, 1); PG8_STAGE(PG8_SB(0, 0), b2, voffB); PG8_STAGE(PG8_SB(0, 1), b2 + hB, voffB); PG8_STAGE(PG8_SA(0, 0), a2, voffA);
;             PG8_WAIT_V(8); PG8_WAIT_L(0); PG8_BAR; PG8_MMA(1, 0, At, B0); PG8_MMA(1, 1, At, B1); PG8_BAR; PG8_SCHED;
;             PG8_LDB(B0, 1, 0); PG8_LDB(B1, 1, 1); PG8_SCHED; PG8_LDA(At, 1, 0); PG8_STAGE(PG8_SA(0, 1), a2 + hA, voffA);
;             PG8_WAIT_V(8); PG8_WAIT_L(0); PG8_BAR; PG8_MMA(0, 0, At, B0); PG8_MMA(0, 1, At, B1); PG8_BAR; PG8_SCHED;
;             PG8_LDA(At, 1, 1); PG8_STAGE(PG8_SB(1, 0), b3, voffB); PG8_STAGE(PG8_SB(1, 1), b3 + hB, voffB); PG8_STAGE(PG8_SA(1, 0), a3, voffA);
;             PG8_WAIT_V(8); PG8_WAIT_L(0); PG8_BAR; PG8_MMA(1, 0, At, B0); PG8_MMA(1, 1, At, B1); PG8_BAR; PG8_SCHED;
	s_setprio 0
	s_mov_b32 m0, s34
	v_lshl_add_u64 v[206:207], v[184:185], 0, s[76:77]
	ds_read_b128 v[168:171], v167 offset:49152
	ds_read_b128 v[172:175], v167 offset:50176
	ds_read_b128 v[176:179], v167 offset:51200
	ds_read_b128 v[180:183], v167 offset:52224
	ds_read_b128 v[188:191], v167 offset:53248
	ds_read_b128 v[192:195], v167 offset:54272
	ds_read_b128 v[196:199], v167 offset:55296
	ds_read_b128 v[200:203], v167 offset:56320
	global_load_lds_dwordx4 v[206:207], off
	v_lshl_add_u64 v[206:207], v[184:185], 0, s[78:79]
	s_mov_b32 m0, s35
	s_nop 0
	global_load_lds_dwordx4 v[206:207], off
	v_lshl_add_u64 v[206:207], v[184:185], 0, s[52:53]
	s_mov_b32 m0, s40
	v_lshl_add_u64 v[184:185], v[184:185], 0, s[54:55]
	global_load_lds_dwordx4 v[206:207], off
	s_mov_b32 m0, s41
	s_nop 0
	global_load_lds_dwordx4 v[184:185], off
	v_lshl_add_u64 v[184:185], v[204:205], 0, s[76:77]
	s_mov_b32 m0, s36
	s_nop 0
	global_load_lds_dwordx4 v[184:185], off
	v_lshl_add_u64 v[184:185], v[204:205], 0, s[78:79]
	s_mov_b32 m0, s37
	s_nop 0
	global_load_lds_dwordx4 v[184:185], off
	s_add_i32 s95, s95, 2
	s_add_u32 s93, s93, 0x8000
	s_addc_u32 s94, s94, 0
	s_mov_b64 s[18:19], s[20:21]
	s_waitcnt vmcnt(8)
	s_waitcnt lgkmcnt(0)
	s_setprio 1
	s_barrier
	v_mfma_f32_16x16x32_bf16 v[62:65], v[130:133], v[168:171], v[62:65]
	v_mfma_f32_16x16x32_bf16 v[58:61], v[138:141], v[168:171], v[58:61]
	v_mfma_f32_16x16x32_bf16 v[46:49], v[130:133], v[176:179], v[46:49]
	v_mfma_f32_16x16x32_bf16 v[42:45], v[138:141], v[176:179], v[42:45]
	v_mfma_f32_16x16x32_bf16 v[30:33], v[130:133], v[188:191], v[30:33]
	v_mfma_f32_16x16x32_bf16 v[26:29], v[138:141], v[188:191], v[26:29]
	v_mfma_f32_16x16x32_bf16 v[14:17], v[130:133], v[196:199], v[14:17]
	v_mfma_f32_16x16x32_bf16 v[10:13], v[138:141], v[196:199], v[10:13]
	v_mfma_f32_16x16x32_bf16 v[62:65], v[134:137], v[172:175], v[62:65]
	v_mfma_f32_16x16x32_bf16 v[58:61], v[142:145], v[172:175], v[58:61]
	v_mfma_f32_16x16x32_bf16 v[46:49], v[134:137], v[180:183], v[46:49]
	v_mfma_f32_16x16x32_bf16 v[42:45], v[142:145], v[180:183], v[42:45]
	v_mfma_f32_16x16x32_bf16 v[30:33], v[134:137], v[192:195], v[30:33]
	v_mfma_f32_16x16x32_bf16 v[26:29], v[142:145], v[192:195], v[26:29]
	v_mfma_f32_16x16x32_bf16 v[14:17], v[134:137], v[200:203], v[14:17]
	v_mfma_f32_16x16x32_bf16 v[10:13], v[142:145], v[200:203], v[10:13]
	v_mfma_f32_16x16x32_bf16 v[54:57], v[146:149], v[168:171], v[54:57]
	v_mfma_f32_16x16x32_bf16 v[50:53], v[156:159], v[168:171], v[50:53]
	v_mfma_f32_16x16x32_bf16 v[38:41], v[146:149], v[176:179], v[38:41]
	v_mfma_f32_16x16x32_bf16 v[34:37], v[156:159], v[176:179], v[34:37]
	v_mfma_f32_16x16x32_bf16 v[22:25], v[146:149], v[188:191], v[22:25]
	v_mfma_f32_16x16x32_bf16 v[18:21], v[156:159], v[188:191], v[18:21]
	v_mfma_f32_16x16x32_bf16 v[6:9], v[146:149], v[196:199], v[6:9]
	v_mfma_f32_16x16x32_bf16 v[2:5], v[156:159], v[196:199], v[2:5]
	v_mfma_f32_16x16x32_bf16 v[54:57], v[150:153], v[172:175], v[54:57]
	v_mfma_f32_16x16x32_bf16 v[50:53], v[160:163], v[172:175], v[50:53]
	v_mfma_f32_16x16x32_bf16 v[38:41], v[150:153], v[180:183], v[38:41]
	v_mfma_f32_16x16x32_bf16 v[34:37], v[160:163], v[180:183], v[34:37]
	v_mfma_f32_16x16x32_bf16 v[22:25], v[150:153], v[192:195], v[22:25]
	v_mfma_f32_16x16x32_bf16 v[18:21], v[160:163], v[192:195], v[18:21]
	v_mfma_f32_16x16x32_bf16 v[6:9], v[150:153], v[200:203], v[6:9]
	v_mfma_f32_16x16x32_bf16 v[2:5], v[160:163], v[200:203], v[2:5]
	s_barrier
	s_setprio 0
	s_cmp_gt_u32 s95, 29
	s_cbranch_scc0 .LBB0_365
	s_and_b64 vcc, exec, s[14:15]
	s_cbranch_vccz .LBB0_368
	s_barrier

; #define PG8_STAGE(bufoff, gbase, unused) do { _Pragma("unroll") for (int _i = 0; _i < 2; ++_i) \
;         __builtin_amdgcn_global_load_lds((const unsigned*)((const char*)(gbase) + voff + _i * 8192), (LAS unsigned*)(lds + (bufoff) + ldsw + _i * 8192), 16, 0, 0); } while (0)
; #define PG8_LDA(dst, b, h) do { _Pragma("unroll") for (int m = 0; m < 4; ++m) _Pragma("unroll") for (int k = 0; k < 2; ++k) dst[m][k] = *(const LAS bf16x8*)(lds + PG8_SA(b, h) + aoff + m * 2048 + (FP8 ? k * 16 : k * 1024)); } while (0)
; #define PG8_LDB(dst, b, h) do { _Pragma("unroll") for (int n = 0; n < 2; ++n) _Pragma("unroll") for (int k = 0; k < 2; ++k) dst[n][k] = *(const LAS bf16x8*)(lds + PG8_SB(b, h) + boff + n * 2048 + (FP8 ? k * 16 : k * 1024)); } while (0)
; #define PG8_WAIT_V(n) asm volatile("s_waitcnt vmcnt(" #n ")" ::: "memory")
; #define PG8_WAIT_L(n) asm volatile("s_waitcnt lgkmcnt(" #n ")" ::: "memory")
; #define PG8_BAR __builtin_amdgcn_s_barrier()
; #define PG8_SCHED __builtin_amdgcn_sched_barrier(0)
; template <class Epi, class Sched, bool ALIGN_EPI, bool SP2, int MODE  >
; __device__ __forceinline__ void gemm_phase(LAS unsigned char* lds, const Gemm g, const Sched S, const Epi E, unsigned long long& probe_acc, int epi_id, int wv) {
;     ...
;         for (int t = 0; t < nt; t += 2) {
;             const bool last = (t == nt - 2);
;             const char* a1 = cA + (size_t)(t + 1) * kstep;
;             const char* a2 = last ? nA : cA + (size_t)(t + 2) * kstep; const char* b2 = last ? nB : cB + (size_t)(t + 2) * kstep;
;             const char* a3 = a2 + kstep; const char* b3 = b2 + kstep;
;             if constexpr (SP2) {
;             PG8_LDB(B0, 0, 0); PG8_LDB(B1, 0, 1); PG8_SCHED; PG8_LDA(At, 0, 0); PG8_STAGE(PG8_SA(1, 1), a1 + hA, voffA);
;             PG8_WAIT_V(8); PG8_WAIT_L(0); PG8_BAR; PG8_MMA(0, 0, At, B0); PG8_MMA(0, 1, At, B1); PG8_BAR; PG8_SCHED;
;             PG8_LDA(At, 0, 1); PG8_STAGE(PG8_SB(0, 0), b2, voffB); PG8_STAGE(PG8_SB(0, 1), b2 + hB, voffB); PG8_STAGE(PG8_SA(0, 0), a2, voffA);
;             PG8_WAIT_V(8); PG8_WAIT_L(0); PG8_BAR; PG8_MMA(1, 0, At, B0); PG8_MMA(1, 1, At, B1); PG8_BAR; PG8_SCHED;
.LBB0_674:
	v_add_u32_e32 v142, s15, v193
	v_add_u32_e32 v156, s39, v193
	ds_read_b128 v[130:133], v142
	ds_read_b128 v[134:137], v142 offset:1024
	ds_read_b128 v[138:141], v142 offset:2048
	ds_read_b128 v[142:145], v142 offset:3072
	ds_read_b128 v[146:149], v156
	ds_read_b128 v[150:153], v156 offset:1024
	ds_read_b128 v[158:161], v156 offset:2048
	ds_read_b128 v[162:165], v156 offset:3072
	s_add_i32 s40, s6, 2
	s_cmp_eq_u32 s93, s6
	s_cselect_b32 s6, s34, s10
	s_cselect_b32 s9, s87, s5
	s_cselect_b32 s8, s86, s4
	s_cselect_b32 s7, s35, s11
	s_movk_i32 vcc_lo, 0xc000
	v_lshl_add_u64 v[190:191], s[4:5], 0, v[154:155]
	s_mov_b32 vcc_hi, -1
	v_lshl_add_u64 v[196:197], v[190:191], 0, vcc
	s_movk_i32 vcc_lo, 0xe000
	s_add_i32 m0, s88, 0xc000
	s_mov_b32 vcc_hi, -1
	ds_read_b128 v[166:169], v194
	ds_read_b128 v[170:173], v194 offset:1024
	ds_read_b128 v[174:177], v194 offset:2048
	ds_read_b128 v[178:181], v194 offset:3072
	ds_read_b128 v[182:185], v194 offset:4096
	ds_read_b128 v[186:189], v194 offset:5120
	ds_read_b128 v[200:203], v194 offset:6144
	ds_read_b128 v[204:207], v194 offset:7168
	global_load_lds_dwordx4 v[196:197], off
	v_lshl_add_u64 v[190:191], v[190:191], 0, vcc
	s_add_i32 m0, s88, 0xe000
	s_nop 0
	global_load_lds_dwordx4 v[190:191], off
	s_waitcnt vmcnt(8)
	s_waitcnt lgkmcnt(0)
	s_setprio 1
	s_barrier
	v_mfma_f32_16x16x32_bf16 v[126:129], v[130:133], v[166:169], v[126:129]
	v_mfma_f32_16x16x32_bf16 v[122:125], v[138:141], v[166:169], v[122:125]
	v_mfma_f32_16x16x32_bf16 v[118:121], v[130:133], v[174:177], v[118:121]
	v_mfma_f32_16x16x32_bf16 v[114:117], v[138:141], v[174:177], v[114:117]
	v_mfma_f32_16x16x32_bf16 v[110:113], v[130:133], v[182:185], v[110:113]
	v_mfma_f32_16x16x32_bf16 v[106:109], v[138:141], v[182:185], v[106:109]
	v_mfma_f32_16x16x32_bf16 v[102:105], v[130:133], v[200:203], v[102:105]
	v_mfma_f32_16x16x32_bf16 v[98:101], v[138:141], v[200:203], v[98:101]
	v_mfma_f32_16x16x32_bf16 v[126:129], v[134:137], v[170:173], v[126:129]
	v_mfma_f32_16x16x32_bf16 v[122:125], v[142:145], v[170:173], v[122:125]
	v_mfma_f32_16x16x32_bf16 v[118:121], v[134:137], v[178:181], v[118:121]
	v_mfma_f32_16x16x32_bf16 v[114:117], v[142:145], v[178:181], v[114:117]
	v_mfma_f32_16x16x32_bf16 v[110:113], v[134:137], v[186:189], v[110:113]
	v_mfma_f32_16x16x32_bf16 v[106:109], v[142:145], v[186:189], v[106:109]
	v_mfma_f32_16x16x32_bf16 v[102:105], v[134:137], v[204:207], v[102:105]
	v_mfma_f32_16x16x32_bf16 v[98:101], v[142:145], v[204:207], v[98:101]
	v_mfma_f32_16x16x32_bf16 v[62:65], v[146:149], v[166:169], v[62:65]
	v_mfma_f32_16x16x32_bf16 v[58:61], v[158:161], v[166:169], v[58:61]
	v_mfma_f32_16x16x32_bf16 v[54:57], v[146:149], v[174:177], v[54:57]
	v_mfma_f32_16x16x32_bf16 v[50:53], v[158:161], v[174:177], v[50:53]
	v_mfma_f32_16x16x32_bf16 v[46:49], v[146:149], v[182:185], v[46:49]
	v_mfma_f32_16x16x32_bf16 v[42:45], v[158:161], v[182:185], v[42:45]
	v_mfma_f32_16x16x32_bf16 v[38:41], v[146:149], v[200:203], v[38:41]
	v_mfma_f32_16x16x32_bf16 v[34:37], v[158:161], v[200:203], v[34:37]
	v_mfma_f32_16x16x32_bf16 v[62:65], v[150:153], v[170:173], v[62:65]
	v_mfma_f32_16x16x32_bf16 v[58:61], v[162:165], v[170:173], v[58:61]
	v_mfma_f32_16x16x32_bf16 v[54:57], v[150:153], v[178:181], v[54:57]
	v_mfma_f32_16x16x32_bf16 v[50:53], v[162:165], v[178:181], v[50:53]
	v_mfma_f32_16x16x32_bf16 v[46:49], v[150:153], v[186:189], v[46:49]
	v_mfma_f32_16x16x32_bf16 v[42:45], v[162:165], v[186:189], v[42:45]
	v_mfma_f32_16x16x32_bf16 v[38:41], v[150:153], v[204:207], v[38:41]
	v_mfma_f32_16x16x32_bf16 v[34:37], v[162:165], v[204:207], v[34:37]
	s_barrier
	s_setprio 0
	s_mov_b32 m0, s26
	v_lshl_add_u64 v[190:191], s[6:7], 0, v[0:1]
	s_add_u32 vcc_lo, s6, s13
	ds_read_b128 v[166:169], v194 offset:16384
	ds_read_b128 v[170:173], v194 offset:17408
	ds_read_b128 v[174:177], v194 offset:18432
	ds_read_b128 v[178:181], v194 offset:19456
	ds_read_b128 v[182:185], v194 offset:20480
	ds_read_b128 v[186:189], v194 offset:21504
	ds_read_b128 v[200:203], v194 offset:22528
	ds_read_b128 v[204:207], v194 offset:23552
	global_load_lds_dwordx4 v[190:191], off
	v_lshl_add_u64 v[190:191], v[190:191], 0, s[70:71]
	s_mov_b32 m0, s27
	s_addc_u32 vcc_hi, s7, 0
	global_load_lds_dwordx4 v[190:191], off
	v_lshl_add_u64 v[190:191], vcc, 0, v[0:1]
	s_mov_b32 m0, s84
	s_nop 0
	global_load_lds_dwordx4 v[190:191], off
	v_lshl_add_u64 v[190:191], v[190:191], 0, s[70:71]
	s_mov_b32 m0, s85
	s_nop 0
	global_load_lds_dwordx4 v[190:191], off
	v_lshl_add_u64 v[190:191], s[8:9], 0, v[0:1]
	s_mov_b32 m0, s88
	v_lshl_add_u64 v[196:197], v[190:191], 0, s[70:71]
	global_load_lds_dwordx4 v[190:191], off
	s_mov_b32 m0, s89
	s_nop 0
	global_load_lds_dwordx4 v[196:197], off
	s_waitcnt vmcnt(8)
	s_waitcnt lgkmcnt(0)
	s_setprio 1
	s_barrier
; #define PG8_STAGE(bufoff, gbase, unused) do { _Pragma("unroll") for (int _i = 0; _i < 2; ++_i) \
;         __builtin_amdgcn_global_load_lds((const unsigned*)((const char*)(gbase) + voff + _i * 8192), (LAS unsigned*)(lds + (bufoff) + ldsw + _i * 8192), 16, 0, 0); } while (0)
; #define PG8_LDA(dst, b, h) do { _Pragma("unroll") for (int m = 0; m < 4; ++m) _Pragma("unroll") for (int k = 0; k < 2; ++k) dst[m][k] = *(const LAS bf16x8*)(lds + PG8_SA(b, h) + aoff + m * 2048 + (FP8 ? k * 16 : k * 1024)); } while (0)
; #define PG8_LDB(dst, b, h) do { _Pragma("unroll") for (int n = 0; n < 2; ++n) _Pragma("unroll") for (int k = 0; k < 2; ++k) dst[n][k] = *(const LAS bf16x8*)(lds + PG8_SB(b, h) + boff + n * 2048 + (FP8 ? k * 16 : k * 1024)); } while (0)
; #define PG8_WAIT_V(n) asm volatile("s_waitcnt vmcnt(" #n ")" ::: "memory")
; #define PG8_WAIT_L(n) asm volatile("s_waitcnt lgkmcnt(" #n ")" ::: "memory")
; #define PG8_BAR __builtin_amdgcn_s_barrier()
; #define PG8_SCHED __builtin_amdgcn_sched_barrier(0)
; template <class Epi, class Sched, bool ALIGN_EPI, bool SP2, int MODE  >
; __device__ __forceinline__ void gemm_phase(LAS unsigned char* lds, const Gemm g, const Sched S, const Epi E, unsigned long long& probe_acc, int epi_id, int wv) {
;     ...
;             PG8_WAIT_V(8); PG8_WAIT_L(0); PG8_BAR; PG8_MMA(1, 0, At, B0); PG8_MMA(1, 1, At, B1); PG8_BAR; PG8_SCHED;
;             PG8_LDB(B0, 1, 0); PG8_LDB(B1, 1, 1); PG8_SCHED; PG8_LDA(At, 1, 0); PG8_STAGE(PG8_SA(0, 1), a2 + hA, voffA);
;             PG8_WAIT_V(8); PG8_WAIT_L(0); PG8_BAR; PG8_MMA(0, 0, At, B0); PG8_MMA(0, 1, At, B1); PG8_BAR; PG8_SCHED;
	v_mfma_f32_16x16x32_bf16 v[94:97], v[130:133], v[166:169], v[94:97]
	v_mfma_f32_16x16x32_bf16 v[90:93], v[138:141], v[166:169], v[90:93]
	v_mfma_f32_16x16x32_bf16 v[86:89], v[130:133], v[174:177], v[86:89]
	v_mfma_f32_16x16x32_bf16 v[82:85], v[138:141], v[174:177], v[82:85]
	v_mfma_f32_16x16x32_bf16 v[78:81], v[130:133], v[182:185], v[78:81]
	v_mfma_f32_16x16x32_bf16 v[74:77], v[138:141], v[182:185], v[74:77]
	v_mfma_f32_16x16x32_bf16 v[70:73], v[130:133], v[200:203], v[70:73]
	v_mfma_f32_16x16x32_bf16 v[66:69], v[138:141], v[200:203], v[66:69]
	v_mfma_f32_16x16x32_bf16 v[94:97], v[134:137], v[170:173], v[94:97]
	v_mfma_f32_16x16x32_bf16 v[90:93], v[142:145], v[170:173], v[90:93]
	v_mfma_f32_16x16x32_bf16 v[86:89], v[134:137], v[178:181], v[86:89]
	v_mfma_f32_16x16x32_bf16 v[82:85], v[142:145], v[178:181], v[82:85]
	v_mfma_f32_16x16x32_bf16 v[78:81], v[134:137], v[186:189], v[78:81]
	v_mfma_f32_16x16x32_bf16 v[74:77], v[142:145], v[186:189], v[74:77]
	v_mfma_f32_16x16x32_bf16 v[70:73], v[134:137], v[204:207], v[70:73]
	v_mfma_f32_16x16x32_bf16 v[66:69], v[142:145], v[204:207], v[66:69]
	v_mfma_f32_16x16x32_bf16 v[30:33], v[146:149], v[166:169], v[30:33]
	v_mfma_f32_16x16x32_bf16 v[26:29], v[158:161], v[166:169], v[26:29]
	v_mfma_f32_16x16x32_bf16 v[22:25], v[146:149], v[174:177], v[22:25]
	v_mfma_f32_16x16x32_bf16 v[18:21], v[158:161], v[174:177], v[18:21]
	v_mfma_f32_16x16x32_bf16 v[14:17], v[146:149], v[182:185], v[14:17]
	v_mfma_f32_16x16x32_bf16 v[10:13], v[158:161], v[182:185], v[10:13]
	v_mfma_f32_16x16x32_bf16 v[6:9], v[146:149], v[200:203], v[6:9]
	v_mfma_f32_16x16x32_bf16 v[2:5], v[158:161], v[200:203], v[2:5]
	v_mfma_f32_16x16x32_bf16 v[30:33], v[150:153], v[170:173], v[30:33]
	v_mfma_f32_16x16x32_bf16 v[26:29], v[162:165], v[170:173], v[26:29]
	v_mfma_f32_16x16x32_bf16 v[22:25], v[150:153], v[178:181], v[22:25]
	v_mfma_f32_16x16x32_bf16 v[18:21], v[162:165], v[178:181], v[18:21]
	v_mfma_f32_16x16x32_bf16 v[14:17], v[150:153], v[186:189], v[14:17]
	v_mfma_f32_16x16x32_bf16 v[10:13], v[162:165], v[186:189], v[10:13]
	v_mfma_f32_16x16x32_bf16 v[6:9], v[150:153], v[204:207], v[6:9]
	v_mfma_f32_16x16x32_bf16 v[2:5], v[162:165], v[204:207], v[2:5]
	s_barrier
	s_setprio 0
	v_add_u32_e32 v142, s28, v193
	v_add_u32_e32 v156, s94, v193
	ds_read_b128 v[130:133], v142
	ds_read_b128 v[134:137], v142 offset:1024
	ds_read_b128 v[138:141], v142 offset:2048
	ds_read_b128 v[142:145], v142 offset:3072
	ds_read_b128 v[146:149], v156
	ds_read_b128 v[150:153], v156 offset:1024
	ds_read_b128 v[158:161], v156 offset:2048
	ds_read_b128 v[162:165], v156 offset:3072
	s_add_u32 s8, s8, s36
	s_addc_u32 s9, s9, 0
	s_mov_b32 m0, s29
	v_lshl_add_u64 v[196:197], s[8:9], 0, v[0:1]
	ds_read_b128 v[166:169], v194 offset:32768
	ds_read_b128 v[170:173], v194 offset:33792
	ds_read_b128 v[174:177], v194 offset:34816
	ds_read_b128 v[178:181], v194 offset:35840
	ds_read_b128 v[182:185], v194 offset:36864
	ds_read_b128 v[186:189], v194 offset:37888
	ds_read_b128 v[200:203], v194 offset:38912
	ds_read_b128 v[204:207], v194 offset:39936
	global_load_lds_dwordx4 v[196:197], off
	v_lshl_add_u64 v[196:197], v[196:197], 0, s[70:71]
	s_mov_b32 m0, s92
	s_nop 0
	global_load_lds_dwordx4 v[196:197], off
	s_waitcnt vmcnt(8)
	s_waitcnt lgkmcnt(0)
	s_setprio 1
	s_barrier
	v_mfma_f32_16x16x32_bf16 v[126:129], v[130:133], v[166:169], v[126:129]
	v_mfma_f32_16x16x32_bf16 v[122:125], v[138:141], v[166:169], v[122:125]
	v_mfma_f32_16x16x32_bf16 v[118:121], v[130:133], v[174:177], v[118:121]
	v_mfma_f32_16x16x32_bf16 v[114:117], v[138:141], v[174:177], v[114:117]
	v_mfma_f32_16x16x32_bf16 v[110:113], v[130:133], v[182:185], v[110:113]
	v_mfma_f32_16x16x32_bf16 v[106:109], v[138:141], v[182:185], v[106:109]
	v_mfma_f32_16x16x32_bf16 v[102:105], v[130:133], v[200:203], v[102:105]
	v_mfma_f32_16x16x32_bf16 v[98:101], v[138:141], v[200:203], v[98:101]
	v_mfma_f32_16x16x32_bf16 v[126:129], v[134:137], v[170:173], v[126:129]
	v_mfma_f32_16x16x32_bf16 v[122:125], v[142:145], v[170:173], v[122:125]
	v_mfma_f32_16x16x32_bf16 v[118:121], v[134:137], v[178:181], v[118:121]
	v_mfma_f32_16x16x32_bf16 v[114:117], v[142:145], v[178:181], v[114:117]
	v_mfma_f32_16x16x32_bf16 v[110:113], v[134:137], v[186:189], v[110:113]
	v_mfma_f32_16x16x32_bf16 v[106:109], v[142:145], v[186:189], v[106:109]
	v_mfma_f32_16x16x32_bf16 v[102:105], v[134:137], v[204:207], v[102:105]
	v_mfma_f32_16x16x32_bf16 v[98:101], v[142:145], v[204:207], v[98:101]
	v_mfma_f32_16x16x32_bf16 v[62:65], v[146:149], v[166:169], v[62:65]
	v_mfma_f32_16x16x32_bf16 v[58:61], v[158:161], v[166:169], v[58:61]
	v_mfma_f32_16x16x32_bf16 v[54:57], v[146:149], v[174:177], v[54:57]
	v_mfma_f32_16x16x32_bf16 v[50:53], v[158:161], v[174:177], v[50:53]
	v_mfma_f32_16x16x32_bf16 v[46:49], v[146:149], v[182:185], v[46:49]
	v_mfma_f32_16x16x32_bf16 v[42:45], v[158:161], v[182:185], v[42:45]
	v_mfma_f32_16x16x32_bf16 v[38:41], v[146:149], v[200:203], v[38:41]
	v_mfma_f32_16x16x32_bf16 v[34:37], v[158:161], v[200:203], v[34:37]
	v_mfma_f32_16x16x32_bf16 v[62:65], v[150:153], v[170:173], v[62:65]
	v_mfma_f32_16x16x32_bf16 v[58:61], v[162:165], v[170:173], v[58:61]
	v_mfma_f32_16x16x32_bf16 v[54:57], v[150:153], v[178:181], v[54:57]
	v_mfma_f32_16x16x32_bf16 v[50:53], v[162:165], v[178:181], v[50:53]
	v_mfma_f32_16x16x32_bf16 v[46:49], v[150:153], v[186:189], v[46:49]
	v_mfma_f32_16x16x32_bf16 v[42:45], v[162:165], v[186:189], v[42:45]
	v_mfma_f32_16x16x32_bf16 v[38:41], v[150:153], v[204:207], v[38:41]
	v_mfma_f32_16x16x32_bf16 v[34:37], v[162:165], v[204:207], v[34:37]
	s_barrier
; #define PG8_STAGE(bufoff, gbase, unused) do { _Pragma("unroll") for (int _i = 0; _i < 2; ++_i) \
;         __builtin_amdgcn_global_load_lds((const unsigned*)((const char*)(gbase) + voff + _i * 8192), (LAS unsigned*)(lds + (bufoff) + ldsw + _i * 8192), 16, 0, 0); } while (0)
; #define PG8_LDA(dst, b, h) do { _Pragma("unroll") for (int m = 0; m < 4; ++m) _Pragma("unroll") for (int k = 0; k < 2; ++k) dst[m][k] = *(const LAS bf16x8*)(lds + PG8_SA(b, h) + aoff + m * 2048 + (FP8 ? k * 16 : k * 1024)); } while (0)
; #define PG8_LDB(dst, b, h) do { _Pragma("unroll") for (int n = 0; n < 2; ++n) _Pragma("unroll") for (int k = 0; k < 2; ++k) dst[n][k] = *(const LAS bf16x8*)(lds + PG8_SB(b, h) + boff + n * 2048 + (FP8 ? k * 16 : k * 1024)); } while (0)
; template <class Epi, class Sched, bool ALIGN_EPI, bool SP2, int MODE  >
; __device__ __forceinline__ void gemm_phase(LAS unsigned char* lds, const Gemm g, const Sched S, const Epi E, unsigned long long& probe_acc, int epi_id, int wv) {
;     ...
;         for (int t = 0; t < nt; t += 2) {
;             const bool last = (t == nt - 2);
;             const char* a1 = cA + (size_t)(t + 1) * kstep;
;             const char* a2 = last ? nA : cA + (size_t)(t + 2) * kstep; const char* b2 = last ? nB : cB + (size_t)(t + 2) * kstep;
;             const char* a3 = a2 + kstep; const char* b3 = b2 + kstep;
;             if constexpr (SP2) {
;             PG8_LDB(B0, 0, 0); PG8_LDB(B1, 0, 1); PG8_SCHED; PG8_LDA(At, 0, 0); PG8_STAGE(PG8_SA(1, 1), a1 + hA, voffA);
;             PG8_WAIT_V(8); PG8_WAIT_L(0); PG8_BAR; PG8_MMA(0, 0, At, B0); PG8_MMA(0, 1, At, B1); PG8_BAR; PG8_SCHED;
;             PG8_LDA(At, 0, 1); PG8_STAGE(PG8_SB(0, 0), b2, voffB); PG8_STAGE(PG8_SB(0, 1), b2 + hB, voffB); PG8_STAGE(PG8_SA(0, 0), a2, voffA);
;             PG8_WAIT_V(8); PG8_WAIT_L(0); PG8_BAR; PG8_MMA(1, 0, At, B0); PG8_MMA(1, 1, At, B1); PG8_BAR; PG8_SCHED;
;             PG8_LDB(B0, 1, 0); PG8_LDB(B1, 1, 1); PG8_SCHED; PG8_LDA(At, 1, 0); PG8_STAGE(PG8_SA(0, 1), a2 + hA, voffA);
;             PG8_WAIT_V(8); PG8_WAIT_L(0); PG8_BAR; PG8_MMA(0, 0, At, B0); PG8_MMA(0, 1, At, B1); PG8_BAR; PG8_SCHED;
;             PG8_LDA(At, 1, 1); PG8_STAGE(PG8_SB(1, 0), b3, voffB); PG8_STAGE(PG8_SB(1, 1), b3 + hB, voffB); PG8_STAGE(PG8_SA(1, 0), a3, voffA);
;             PG8_WAIT_V(8); PG8_WAIT_L(0); PG8_BAR; PG8_MMA(1, 0, At, B0); PG8_MMA(1, 1, At, B1); PG8_BAR; PG8_SCHED;
	s_setprio 0
	s_add_u32 s6, s6, 0x4000
	s_addc_u32 s7, s7, 0
	s_mov_b32 m0, s2
	v_lshl_add_u64 v[196:197], s[6:7], 0, v[0:1]
	s_add_u32 s6, s6, s13
	ds_read_b128 v[166:169], v194 offset:49152
	ds_read_b128 v[170:173], v194 offset:50176
	ds_read_b128 v[174:177], v194 offset:51200
	ds_read_b128 v[178:181], v194 offset:52224
	ds_read_b128 v[182:185], v194 offset:53248
	ds_read_b128 v[186:189], v194 offset:54272
	ds_read_b128 v[200:203], v194 offset:55296
	ds_read_b128 v[204:207], v194 offset:56320
	global_load_lds_dwordx4 v[196:197], off
	v_lshl_add_u64 v[196:197], v[196:197], 0, s[70:71]
	s_mov_b32 m0, s3
	s_addc_u32 s7, s7, 0
	global_load_lds_dwordx4 v[196:197], off
	v_lshl_add_u64 v[196:197], s[6:7], 0, v[0:1]
	s_mov_b32 m0, s12
	s_nop 0
	global_load_lds_dwordx4 v[196:197], off
	v_lshl_add_u64 v[196:197], v[196:197], 0, s[70:71]
	s_mov_b32 m0, s95
	s_nop 0
	global_load_lds_dwordx4 v[196:197], off
	v_lshl_add_u64 v[196:197], v[190:191], 0, s[76:77]
	s_mov_b32 m0, s50
	v_lshl_add_u64 v[190:191], v[190:191], 0, s[78:79]
	global_load_lds_dwordx4 v[196:197], off
	s_mov_b32 m0, s51
	s_nop 0
	global_load_lds_dwordx4 v[190:191], off
	s_add_u32 s10, s10, 0x8000
	s_addc_u32 s11, s11, 0
	s_add_u32 s4, s4, 0x8000
	s_addc_u32 s5, s5, 0
	s_mov_b32 s6, s40
	s_waitcnt vmcnt(8)
	s_waitcnt lgkmcnt(0)
	s_setprio 1
	s_barrier
	v_mfma_f32_16x16x32_bf16 v[94:97], v[130:133], v[166:169], v[94:97]
	v_mfma_f32_16x16x32_bf16 v[90:93], v[138:141], v[166:169], v[90:93]
	v_mfma_f32_16x16x32_bf16 v[86:89], v[130:133], v[174:177], v[86:89]
	v_mfma_f32_16x16x32_bf16 v[82:85], v[138:141], v[174:177], v[82:85]
	v_mfma_f32_16x16x32_bf16 v[78:81], v[130:133], v[182:185], v[78:81]
	v_mfma_f32_16x16x32_bf16 v[74:77], v[138:141], v[182:185], v[74:77]
	v_mfma_f32_16x16x32_bf16 v[70:73], v[130:133], v[200:203], v[70:73]
	v_mfma_f32_16x16x32_bf16 v[66:69], v[138:141], v[200:203], v[66:69]
	v_mfma_f32_16x16x32_bf16 v[94:97], v[134:137], v[170:173], v[94:97]
	v_mfma_f32_16x16x32_bf16 v[90:93], v[142:145], v[170:173], v[90:93]
	v_mfma_f32_16x16x32_bf16 v[86:89], v[134:137], v[178:181], v[86:89]
	v_mfma_f32_16x16x32_bf16 v[82:85], v[142:145], v[178:181], v[82:85]
	v_mfma_f32_16x16x32_bf16 v[78:81], v[134:137], v[186:189], v[78:81]
	v_mfma_f32_16x16x32_bf16 v[74:77], v[142:145], v[186:189], v[74:77]
	v_mfma_f32_16x16x32_bf16 v[70:73], v[134:137], v[204:207], v[70:73]
	v_mfma_f32_16x16x32_bf16 v[66:69], v[142:145], v[204:207], v[66:69]
	v_mfma_f32_16x16x32_bf16 v[30:33], v[146:149], v[166:169], v[30:33]
	v_mfma_f32_16x16x32_bf16 v[26:29], v[158:161], v[166:169], v[26:29]
	v_mfma_f32_16x16x32_bf16 v[22:25], v[146:149], v[174:177], v[22:25]
	v_mfma_f32_16x16x32_bf16 v[18:21], v[158:161], v[174:177], v[18:21]
	v_mfma_f32_16x16x32_bf16 v[14:17], v[146:149], v[182:185], v[14:17]
	v_mfma_f32_16x16x32_bf16 v[10:13], v[158:161], v[182:185], v[10:13]
	v_mfma_f32_16x16x32_bf16 v[6:9], v[146:149], v[200:203], v[6:9]
	v_mfma_f32_16x16x32_bf16 v[2:5], v[158:161], v[200:203], v[2:5]
	v_mfma_f32_16x16x32_bf16 v[30:33], v[150:153], v[170:173], v[30:33]
	v_mfma_f32_16x16x32_bf16 v[26:29], v[162:165], v[170:173], v[26:29]
	v_mfma_f32_16x16x32_bf16 v[22:25], v[150:153], v[178:181], v[22:25]
	v_mfma_f32_16x16x32_bf16 v[18:21], v[162:165], v[178:181], v[18:21]
	v_mfma_f32_16x16x32_bf16 v[14:17], v[150:153], v[186:189], v[14:17]
	v_mfma_f32_16x16x32_bf16 v[10:13], v[162:165], v[186:189], v[10:13]
	v_mfma_f32_16x16x32_bf16 v[6:9], v[150:153], v[204:207], v[6:9]
	v_mfma_f32_16x16x32_bf16 v[2:5], v[162:165], v[204:207], v[2:5]
	s_barrier
	s_setprio 0
	s_cmp_ge_u32 s40, s58
	s_cbranch_scc0 .LBB0_674
	v_readlane_b32 s4, v255, 30
	v_readlane_b32 s5, v255, 31
	s_and_b64 vcc, exec, s[4:5]
	s_cbranch_vccz .LBB0_677
	s_barrier

; #define PG8_STAGE(bufoff, gbase, unused) do { _Pragma("unroll") for (int _i = 0; _i < 2; ++_i) \
;         __builtin_amdgcn_global_load_lds((const unsigned*)((const char*)(gbase) + voff + _i * 8192), (LAS unsigned*)(lds + (bufoff) + ldsw + _i * 8192), 16, 0, 0); } while (0)
; #define PG8_LDA(dst, b, h) do { _Pragma("unroll") for (int m = 0; m < 4; ++m) _Pragma("unroll") for (int k = 0; k < 2; ++k) dst[m][k] = *(const LAS bf16x8*)(lds + PG8_SA(b, h) + aoff + m * 2048 + (FP8 ? k * 16 : k * 1024)); } while (0)
; #define PG8_LDB(dst, b, h) do { _Pragma("unroll") for (int n = 0; n < 2; ++n) _Pragma("unroll") for (int k = 0; k < 2; ++k) dst[n][k] = *(const LAS bf16x8*)(lds + PG8_SB(b, h) + boff + n * 2048 + (FP8 ? k * 16 : k * 1024)); } while (0)
; #define PG8_WAIT_V(n) asm volatile("s_waitcnt vmcnt(" #n ")" ::: "memory")
; #define PG8_WAIT_L(n) asm volatile("s_waitcnt lgkmcnt(" #n ")" ::: "memory")
; #define PG8_BAR __builtin_amdgcn_s_barrier()
; #define PG8_SCHED __builtin_amdgcn_sched_barrier(0)
; template <class Epi, class Sched, bool ALIGN_EPI, bool SP2, int MODE  >
; __device__ __forceinline__ void gemm_phase(LAS unsigned char* lds, const Gemm g, const Sched S, const Epi E, unsigned long long& probe_acc, int epi_id, int wv) {
;     ...
;         for (int t = 0; t < nt; t += 2) {
;             const bool last = (t == nt - 2);
;             const char* a1 = cA + (size_t)(t + 1) * kstep;
;             const char* a2 = last ? nA : cA + (size_t)(t + 2) * kstep; const char* b2 = last ? nB : cB + (size_t)(t + 2) * kstep;
;             const char* a3 = a2 + kstep; const char* b3 = b2 + kstep;
;             if constexpr (SP2) {
;             PG8_LDB(B0, 0, 0); PG8_LDB(B1, 0, 1); PG8_SCHED; PG8_LDA(At, 0, 0); PG8_STAGE(PG8_SA(1, 1), a1 + hA, voffA);
;             PG8_WAIT_V(8); PG8_WAIT_L(0); PG8_BAR; PG8_MMA(0, 0, At, B0); PG8_MMA(0, 1, At, B1); PG8_BAR; PG8_SCHED;
;             PG8_LDA(At, 0, 1); PG8_STAGE(PG8_SB(0, 0), b2, voffB); PG8_STAGE(PG8_SB(0, 1), b2 + hB, voffB); PG8_STAGE(PG8_SA(0, 0), a2, voffA);
;             PG8_WAIT_V(8); PG8_WAIT_L(0); PG8_BAR; PG8_MMA(1, 0, At, B0); PG8_MMA(1, 1, At, B1); PG8_BAR; PG8_SCHED;
.LBB0_914:
	v_add_u32_e32 v144, s14, v191
	v_add_u32_e32 v148, s27, v191
	s_add_u32 s8, s4, s6
	ds_read_b128 v[132:135], v144
	v_xor_b32_e32 v154, 16, v144
	ds_read_b128 v[136:139], v154
	ds_read_b128 v[140:143], v144 offset:2048
	ds_read_b128 v[144:147], v154 offset:2048
	ds_read_b128 v[156:159], v148
	v_xor_b32_e32 v154, 16, v148
	ds_read_b128 v[160:163], v154
	ds_read_b128 v[164:167], v148 offset:2048
	ds_read_b128 v[168:171], v154 offset:2048
	s_addc_u32 s9, s5, s7
	s_add_u32 s8, s8, 0x8000
	s_addc_u32 s9, s9, 0
	s_add_u32 s10, s34, s6
	s_addc_u32 s11, s35, s7
	s_cmp_eq_u32 s6, 0xa8000
	s_cselect_b32 s9, s69, s9
	s_cselect_b32 s8, s68, s8
	s_cselect_b32 s11, s91, s11
	s_cselect_b32 s10, s90, s10
	v_lshl_add_u64 v[148:149], v[130:131], 0, s[6:7]
	v_lshl_add_u64 v[150:151], v[148:149], 0, s[76:77]
	s_add_i32 m0, s41, 0xc000
	ds_read_b128 v[172:175], v192
	ds_read_b128 v[176:179], v193
	ds_read_b128 v[180:183], v192 offset:2048
	ds_read_b128 v[184:187], v193 offset:2048
	ds_read_b128 v[212:215], v192 offset:4096
	ds_read_b128 v[216:219], v193 offset:4096
	ds_read_b128 v[220:223], v192 offset:6144
	ds_read_b128 v[224:227], v193 offset:6144
	global_load_lds_dwordx4 v[150:151], off
	v_lshl_add_u64 v[148:149], v[148:149], 0, s[78:79]
	s_add_i32 m0, s41, 0xe000
	s_nop 0
	global_load_lds_dwordx4 v[148:149], off
	s_waitcnt vmcnt(8)
	s_waitcnt lgkmcnt(0)
	s_setprio 1
	s_barrier
	v_mfma_scale_f32_16x16x128_f8f6f4 v[126:129], v[132:139], v[172:179], v[126:129], v208, v208 op_sel_hi:[0,0,0]
	v_mfma_scale_f32_16x16x128_f8f6f4 v[122:125], v[140:147], v[172:179], v[122:125], v208, v208 op_sel_hi:[0,0,0]
	v_mfma_scale_f32_16x16x128_f8f6f4 v[118:121], v[132:139], v[180:187], v[118:121], v208, v208 op_sel_hi:[0,0,0]
	v_mfma_scale_f32_16x16x128_f8f6f4 v[114:117], v[140:147], v[180:187], v[114:117], v208, v208 op_sel_hi:[0,0,0]
	v_mfma_scale_f32_16x16x128_f8f6f4 v[110:113], v[132:139], v[212:219], v[110:113], v208, v208 op_sel_hi:[0,0,0]
	v_mfma_scale_f32_16x16x128_f8f6f4 v[106:109], v[140:147], v[212:219], v[106:109], v208, v208 op_sel_hi:[0,0,0]
	v_mfma_scale_f32_16x16x128_f8f6f4 v[102:105], v[132:139], v[220:227], v[102:105], v208, v208 op_sel_hi:[0,0,0]
	v_mfma_scale_f32_16x16x128_f8f6f4 v[98:101], v[140:147], v[220:227], v[98:101], v208, v208 op_sel_hi:[0,0,0]
	v_mfma_scale_f32_16x16x128_f8f6f4 v[148:151], v[156:163], v[172:179], v[62:65], v208, v208 op_sel_hi:[0,0,0]
	v_mfma_scale_f32_16x16x128_f8f6f4 v[172:175], v[164:171], v[172:179], v[58:61], v208, v208 op_sel_hi:[0,0,0]
	v_mfma_scale_f32_16x16x128_f8f6f4 v[176:179], v[156:163], v[180:187], v[54:57], v208, v208 op_sel_hi:[0,0,0]
	v_mfma_scale_f32_16x16x128_f8f6f4 v[180:183], v[164:171], v[180:187], v[50:53], v208, v208 op_sel_hi:[0,0,0]
	v_mfma_scale_f32_16x16x128_f8f6f4 v[184:187], v[156:163], v[212:219], v[46:49], v208, v208 op_sel_hi:[0,0,0]
	v_mfma_scale_f32_16x16x128_f8f6f4 v[194:197], v[164:171], v[212:219], v[42:45], v208, v208 op_sel_hi:[0,0,0]
	v_mfma_scale_f32_16x16x128_f8f6f4 v[200:203], v[156:163], v[220:227], v[38:41], v208, v208 op_sel_hi:[0,0,0]
	v_mfma_scale_f32_16x16x128_f8f6f4 v[212:215], v[164:171], v[220:227], v[34:37], v208, v208 op_sel_hi:[0,0,0]
	s_barrier
	s_setprio 0
	s_mov_b32 m0, s15
	v_lshl_add_u64 v[152:153], s[10:11], 0, v[0:1]
	s_nop 2
	ds_read_b128 v[34:37], v192 offset:16384
	ds_read_b128 v[38:41], v193 offset:16384
	ds_read_b128 v[42:45], v192 offset:18432
	ds_read_b128 v[46:49], v193 offset:18432
	ds_read_b128 v[50:53], v192 offset:20480
	ds_read_b128 v[54:57], v193 offset:20480
	ds_read_b128 v[58:61], v192 offset:22528
	ds_read_b128 v[62:65], v193 offset:22528
	global_load_lds_dwordx4 v[152:153], off
	v_lshl_add_u64 v[188:189], v[152:153], 0, s[70:71]
	s_mov_b32 m0, s26
	s_nop 0
	global_load_lds_dwordx4 v[188:189], off
	v_lshl_add_u64 v[188:189], v[152:153], 0, s[42:43]
	s_mov_b32 m0, s39
	s_nop 0
	global_load_lds_dwordx4 v[188:189], off
	v_lshl_add_u64 v[188:189], v[152:153], 0, s[48:49]
	s_mov_b32 m0, s40
	s_nop 0
	global_load_lds_dwordx4 v[188:189], off
	v_lshl_add_u64 v[188:189], s[8:9], 0, v[0:1]
	s_mov_b32 m0, s41
	v_lshl_add_u64 v[204:205], v[188:189], 0, s[70:71]
	global_load_lds_dwordx4 v[188:189], off
	s_mov_b32 m0, s84
	s_nop 0
	global_load_lds_dwordx4 v[204:205], off
	s_waitcnt vmcnt(8)
	s_waitcnt lgkmcnt(0)
	s_setprio 1
	s_barrier
	v_mfma_scale_f32_16x16x128_f8f6f4 v[94:97], v[132:139], v[34:41], v[94:97], v208, v208 op_sel_hi:[0,0,0]
	v_mfma_scale_f32_16x16x128_f8f6f4 v[90:93], v[140:147], v[34:41], v[90:93], v208, v208 op_sel_hi:[0,0,0]
	v_mfma_scale_f32_16x16x128_f8f6f4 v[86:89], v[132:139], v[42:49], v[86:89], v208, v208 op_sel_hi:[0,0,0]
	v_mfma_scale_f32_16x16x128_f8f6f4 v[82:85], v[140:147], v[42:49], v[82:85], v208, v208 op_sel_hi:[0,0,0]
	v_mfma_scale_f32_16x16x128_f8f6f4 v[78:81], v[132:139], v[50:57], v[78:81], v208, v208 op_sel_hi:[0,0,0]
	v_mfma_scale_f32_16x16x128_f8f6f4 v[74:77], v[140:147], v[50:57], v[74:77], v208, v208 op_sel_hi:[0,0,0]
	v_mfma_scale_f32_16x16x128_f8f6f4 v[216:219], v[132:139], v[58:65], v[70:73], v208, v208 op_sel_hi:[0,0,0]
	v_mfma_scale_f32_16x16x128_f8f6f4 v[220:223], v[140:147], v[58:65], v[66:69], v208, v208 op_sel_hi:[0,0,0]
	v_mfma_scale_f32_16x16x128_f8f6f4 v[224:227], v[156:163], v[34:41], v[30:33], v208, v208 op_sel_hi:[0,0,0]
	v_mfma_scale_f32_16x16x128_f8f6f4 v[228:231], v[164:171], v[34:41], v[26:29], v208, v208 op_sel_hi:[0,0,0]
	v_mfma_scale_f32_16x16x128_f8f6f4 v[232:235], v[156:163], v[42:49], v[22:25], v208, v208 op_sel_hi:[0,0,0]
	v_mfma_scale_f32_16x16x128_f8f6f4 v[236:239], v[164:171], v[42:49], v[18:21], v208, v208 op_sel_hi:[0,0,0]
	v_mfma_scale_f32_16x16x128_f8f6f4 v[240:243], v[156:163], v[50:57], v[14:17], v208, v208 op_sel_hi:[0,0,0]
	v_mfma_scale_f32_16x16x128_f8f6f4 v[244:247], v[164:171], v[50:57], v[10:13], v208, v208 op_sel_hi:[0,0,0]
	v_mfma_scale_f32_16x16x128_f8f6f4 v[248:251], v[156:163], v[58:65], v[6:9], v208, v208 op_sel_hi:[0,0,0]
	v_mfma_scale_f32_16x16x128_f8f6f4 v[204:207], v[164:171], v[58:65], v[2:5], v208, v208 op_sel_hi:[0,0,0]
	s_barrier
; #define PG8_STAGE(bufoff, gbase, unused) do { _Pragma("unroll") for (int _i = 0; _i < 2; ++_i) \
;         __builtin_amdgcn_global_load_lds((const unsigned*)((const char*)(gbase) + voff + _i * 8192), (LAS unsigned*)(lds + (bufoff) + ldsw + _i * 8192), 16, 0, 0); } while (0)
; #define PG8_LDA(dst, b, h) do { _Pragma("unroll") for (int m = 0; m < 4; ++m) _Pragma("unroll") for (int k = 0; k < 2; ++k) dst[m][k] = *(const LAS bf16x8*)(lds + PG8_SA(b, h) + aoff + m * 2048 + (FP8 ? k * 16 : k * 1024)); } while (0)
; #define PG8_LDB(dst, b, h) do { _Pragma("unroll") for (int n = 0; n < 2; ++n) _Pragma("unroll") for (int k = 0; k < 2; ++k) dst[n][k] = *(const LAS bf16x8*)(lds + PG8_SB(b, h) + boff + n * 2048 + (FP8 ? k * 16 : k * 1024)); } while (0)
; template <class Epi, class Sched, bool ALIGN_EPI, bool SP2, int MODE  >
; __device__ __forceinline__ void gemm_phase(LAS unsigned char* lds, const Gemm g, const Sched S, const Epi E, unsigned long long& probe_acc, int epi_id, int wv) {
;     ...
;         for (int t = 0; t < nt; t += 2) {
;             const bool last = (t == nt - 2);
;             const char* a1 = cA + (size_t)(t + 1) * kstep;
;             const char* a2 = last ? nA : cA + (size_t)(t + 2) * kstep; const char* b2 = last ? nB : cB + (size_t)(t + 2) * kstep;
;             const char* a3 = a2 + kstep; const char* b3 = b2 + kstep;
;             if constexpr (SP2) {
;             PG8_LDB(B0, 0, 0); PG8_LDB(B1, 0, 1); PG8_SCHED; PG8_LDA(At, 0, 0); PG8_STAGE(PG8_SA(1, 1), a1 + hA, voffA);
;             PG8_WAIT_V(8); PG8_WAIT_L(0); PG8_BAR; PG8_MMA(0, 0, At, B0); PG8_MMA(0, 1, At, B1); PG8_BAR; PG8_SCHED;
;             PG8_LDA(At, 0, 1); PG8_STAGE(PG8_SB(0, 0), b2, voffB); PG8_STAGE(PG8_SB(0, 1), b2 + hB, voffB); PG8_STAGE(PG8_SA(0, 0), a2, voffA);
;             PG8_WAIT_V(8); PG8_WAIT_L(0); PG8_BAR; PG8_MMA(1, 0, At, B0); PG8_MMA(1, 1, At, B1); PG8_BAR; PG8_SCHED;
;             PG8_LDB(B0, 1, 0); PG8_LDB(B1, 1, 1); PG8_SCHED; PG8_LDA(At, 1, 0); PG8_STAGE(PG8_SA(0, 1), a2 + hA, voffA);
;             PG8_WAIT_V(8); PG8_WAIT_L(0); PG8_BAR; PG8_MMA(0, 0, At, B0); PG8_MMA(0, 1, At, B1); PG8_BAR; PG8_SCHED;
;             PG8_LDA(At, 1, 1); PG8_STAGE(PG8_SB(1, 0), b3, voffB); PG8_STAGE(PG8_SB(1, 1), b3 + hB, voffB); PG8_STAGE(PG8_SA(1, 0), a3, voffA);
;             PG8_WAIT_V(8); PG8_WAIT_L(0); PG8_BAR; PG8_MMA(1, 0, At, B0); PG8_MMA(1, 1, At, B1); PG8_BAR; PG8_SCHED;
	s_setprio 0
	s_nop 1
	v_add_u32_e32 v14, s89, v191
	v_add_u32_e32 v18, s29, v191
	s_nop 0
	ds_read_b128 v[2:5], v14
	v_xor_b32_e32 v154, 16, v14
	ds_read_b128 v[6:9], v154
	ds_read_b128 v[10:13], v14 offset:2048
	ds_read_b128 v[14:17], v154 offset:2048
	ds_read_b128 v[132:135], v18
	v_xor_b32_e32 v154, 16, v18
	ds_read_b128 v[136:139], v154
	ds_read_b128 v[140:143], v18 offset:2048
	ds_read_b128 v[144:147], v154 offset:2048
	s_add_u32 s8, s8, s12
	s_addc_u32 s9, s9, 0
	s_mov_b32 m0, s85
	v_lshl_add_u64 v[42:43], s[8:9], 0, v[0:1]
	ds_read_b128 v[18:21], v192 offset:32768
	ds_read_b128 v[22:25], v193 offset:32768
	ds_read_b128 v[26:29], v192 offset:34816
	ds_read_b128 v[30:33], v193 offset:34816
	ds_read_b128 v[34:37], v192 offset:36864
	ds_read_b128 v[38:41], v193 offset:36864
	ds_read_b128 v[66:69], v192 offset:38912
	ds_read_b128 v[70:73], v193 offset:38912
	global_load_lds_dwordx4 v[42:43], off
	v_lshl_add_u64 v[42:43], v[42:43], 0, s[70:71]
	s_mov_b32 m0, s88
	s_nop 0
	global_load_lds_dwordx4 v[42:43], off
	s_waitcnt vmcnt(8)
	s_waitcnt lgkmcnt(0)
	s_setprio 1
	s_barrier
	v_mfma_scale_f32_16x16x128_f8f6f4 v[126:129], v[2:9], v[18:25], v[126:129], v208, v208 op_sel_hi:[0,0,0]
	v_mfma_scale_f32_16x16x128_f8f6f4 v[122:125], v[10:17], v[18:25], v[122:125], v208, v208 op_sel_hi:[0,0,0]
	v_mfma_scale_f32_16x16x128_f8f6f4 v[118:121], v[2:9], v[26:33], v[118:121], v208, v208 op_sel_hi:[0,0,0]
	v_mfma_scale_f32_16x16x128_f8f6f4 v[114:117], v[10:17], v[26:33], v[114:117], v208, v208 op_sel_hi:[0,0,0]
	v_mfma_scale_f32_16x16x128_f8f6f4 v[110:113], v[2:9], v[34:41], v[110:113], v208, v208 op_sel_hi:[0,0,0]
	v_mfma_scale_f32_16x16x128_f8f6f4 v[106:109], v[10:17], v[34:41], v[106:109], v208, v208 op_sel_hi:[0,0,0]
	v_mfma_scale_f32_16x16x128_f8f6f4 v[102:105], v[2:9], v[66:73], v[102:105], v208, v208 op_sel_hi:[0,0,0]
	v_mfma_scale_f32_16x16x128_f8f6f4 v[98:101], v[10:17], v[66:73], v[98:101], v208, v208 op_sel_hi:[0,0,0]
	v_mfma_scale_f32_16x16x128_f8f6f4 v[62:65], v[132:139], v[18:25], v[148:151], v208, v208 op_sel_hi:[0,0,0]
	v_mfma_scale_f32_16x16x128_f8f6f4 v[58:61], v[140:147], v[18:25], v[172:175], v208, v208 op_sel_hi:[0,0,0]
	v_mfma_scale_f32_16x16x128_f8f6f4 v[54:57], v[132:139], v[26:33], v[176:179], v208, v208 op_sel_hi:[0,0,0]
	v_mfma_scale_f32_16x16x128_f8f6f4 v[50:53], v[140:147], v[26:33], v[180:183], v208, v208 op_sel_hi:[0,0,0]
	v_mfma_scale_f32_16x16x128_f8f6f4 v[46:49], v[132:139], v[34:41], v[184:187], v208, v208 op_sel_hi:[0,0,0]
	v_mfma_scale_f32_16x16x128_f8f6f4 v[42:45], v[140:147], v[34:41], v[194:197], v208, v208 op_sel_hi:[0,0,0]
	v_mfma_scale_f32_16x16x128_f8f6f4 v[38:41], v[132:139], v[66:73], v[200:203], v208, v208 op_sel_hi:[0,0,0]
	v_mfma_scale_f32_16x16x128_f8f6f4 v[34:37], v[140:147], v[66:73], v[212:215], v208, v208 op_sel_hi:[0,0,0]
	s_barrier
	s_setprio 0
	s_mov_b32 m0, s92
	v_lshl_add_u64 v[26:27], v[152:153], 0, s[76:77]
	ds_read_b128 v[18:21], v192 offset:49152
	ds_read_b128 v[22:25], v193 offset:49152
	ds_read_b128 v[156:159], v192 offset:51200
	ds_read_b128 v[160:163], v193 offset:51200
	ds_read_b128 v[164:167], v192 offset:53248
	ds_read_b128 v[168:171], v193 offset:53248
	ds_read_b128 v[172:175], v192 offset:55296
	ds_read_b128 v[176:179], v193 offset:55296
	global_load_lds_dwordx4 v[26:27], off
	v_lshl_add_u64 v[26:27], v[152:153], 0, s[78:79]
	s_mov_b32 m0, s93
	s_nop 0
	global_load_lds_dwordx4 v[26:27], off
	v_lshl_add_u64 v[26:27], v[152:153], 0, s[44:45]
	s_mov_b32 m0, s0
	s_nop 0
	global_load_lds_dwordx4 v[26:27], off
	v_lshl_add_u64 v[26:27], v[152:153], 0, s[56:57]
	s_mov_b32 m0, s1
	s_nop 0
	global_load_lds_dwordx4 v[26:27], off
	v_lshl_add_u64 v[26:27], v[188:189], 0, s[76:77]
	s_mov_b32 m0, s94
	s_nop 0
	global_load_lds_dwordx4 v[26:27], off
	v_lshl_add_u64 v[26:27], v[188:189], 0, s[78:79]
	s_mov_b32 m0, s95
	s_nop 0
	global_load_lds_dwordx4 v[26:27], off
	s_add_i32 s46, s46, 2
	s_add_u32 s6, s6, 0x8000
	s_addc_u32 s7, s7, 0
	s_waitcnt vmcnt(8)
	s_waitcnt lgkmcnt(0)
	s_setprio 1
	s_barrier
	v_mfma_scale_f32_16x16x128_f8f6f4 v[94:97], v[2:9], v[18:25], v[94:97], v208, v208 op_sel_hi:[0,0,0]
	v_mfma_scale_f32_16x16x128_f8f6f4 v[90:93], v[10:17], v[18:25], v[90:93], v208, v208 op_sel_hi:[0,0,0]
	v_mfma_scale_f32_16x16x128_f8f6f4 v[86:89], v[2:9], v[156:163], v[86:89], v208, v208 op_sel_hi:[0,0,0]
	v_mfma_scale_f32_16x16x128_f8f6f4 v[82:85], v[10:17], v[156:163], v[82:85], v208, v208 op_sel_hi:[0,0,0]
	v_mfma_scale_f32_16x16x128_f8f6f4 v[78:81], v[2:9], v[164:171], v[78:81], v208, v208 op_sel_hi:[0,0,0]
	v_mfma_scale_f32_16x16x128_f8f6f4 v[74:77], v[10:17], v[164:171], v[74:77], v208, v208 op_sel_hi:[0,0,0]
	v_mfma_scale_f32_16x16x128_f8f6f4 v[70:73], v[2:9], v[172:179], v[216:219], v208, v208 op_sel_hi:[0,0,0]
	v_mfma_scale_f32_16x16x128_f8f6f4 v[66:69], v[10:17], v[172:179], v[220:223], v208, v208 op_sel_hi:[0,0,0]
	v_mfma_scale_f32_16x16x128_f8f6f4 v[30:33], v[132:139], v[18:25], v[224:227], v208, v208 op_sel_hi:[0,0,0]
	v_mfma_scale_f32_16x16x128_f8f6f4 v[26:29], v[140:147], v[18:25], v[228:231], v208, v208 op_sel_hi:[0,0,0]
	v_mfma_scale_f32_16x16x128_f8f6f4 v[22:25], v[132:139], v[156:163], v[232:235], v208, v208 op_sel_hi:[0,0,0]
	v_mfma_scale_f32_16x16x128_f8f6f4 v[18:21], v[140:147], v[156:163], v[236:239], v208, v208 op_sel_hi:[0,0,0]
	v_mfma_scale_f32_16x16x128_f8f6f4 v[14:17], v[132:139], v[164:171], v[240:243], v208, v208 op_sel_hi:[0,0,0]
	v_mfma_scale_f32_16x16x128_f8f6f4 v[10:13], v[140:147], v[164:171], v[244:247], v208, v208 op_sel_hi:[0,0,0]
	v_mfma_scale_f32_16x16x128_f8f6f4 v[6:9], v[132:139], v[172:179], v[248:251], v208, v208 op_sel_hi:[0,0,0]
	v_mfma_scale_f32_16x16x128_f8f6f4 v[2:5], v[140:147], v[172:179], v[204:207], v208, v208 op_sel_hi:[0,0,0]
	s_barrier
	s_setprio 0
	s_cmp_gt_u32 s46, 41
	s_cbranch_scc0 .LBB0_914
	v_readlane_b32 s4, v255, 1
	v_readlane_b32 s5, v255, 2
	s_and_b64 vcc, exec, s[4:5]
	s_cbranch_vccz .LBB0_917
	s_barrier

; #define PG8_STAGE(bufoff, gbase, unused) do { _Pragma("unroll") for (int _i = 0; _i < 2; ++_i) \
;         __builtin_amdgcn_global_load_lds((const unsigned*)((const char*)(gbase) + voff + _i * 8192), (LAS unsigned*)(lds + (bufoff) + ldsw + _i * 8192), 16, 0, 0); } while (0)
; #define PG8_LDA(dst, b, h) do { _Pragma("unroll") for (int m = 0; m < 4; ++m) _Pragma("unroll") for (int k = 0; k < 2; ++k) dst[m][k] = *(const LAS bf16x8*)(lds + PG8_SA(b, h) + aoff + m * 2048 + (FP8 ? k * 16 : k * 1024)); } while (0)
; #define PG8_LDB(dst, b, h) do { _Pragma("unroll") for (int n = 0; n < 2; ++n) _Pragma("unroll") for (int k = 0; k < 2; ++k) dst[n][k] = *(const LAS bf16x8*)(lds + PG8_SB(b, h) + boff + n * 2048 + (FP8 ? k * 16 : k * 1024)); } while (0)
; #define PG8_WAIT_V(n) asm volatile("s_waitcnt vmcnt(" #n ")" ::: "memory")
; #define PG8_WAIT_L(n) asm volatile("s_waitcnt lgkmcnt(" #n ")" ::: "memory")
; #define PG8_BAR __builtin_amdgcn_s_barrier()
; #define PG8_SCHED __builtin_amdgcn_sched_barrier(0)
; template <class Epi, class Sched, bool ALIGN_EPI, bool SP2, int MODE  >
; __device__ __forceinline__ void gemm_phase(LAS unsigned char* lds, const Gemm g, const Sched S, const Epi E, unsigned long long& probe_acc, int epi_id, int wv) {
;     ...
;         for (int t = 0; t < nt; t += 2) {
;             const bool last = (t == nt - 2);
;             const char* a1 = cA + (size_t)(t + 1) * kstep;
;             const char* a2 = last ? nA : cA + (size_t)(t + 2) * kstep; const char* b2 = last ? nB : cB + (size_t)(t + 2) * kstep;
;             const char* a3 = a2 + kstep; const char* b3 = b2 + kstep;
;             if constexpr (SP2) {
;             PG8_LDB(B0, 0, 0); PG8_LDB(B1, 0, 1); PG8_SCHED; PG8_LDA(At, 0, 0); PG8_STAGE(PG8_SA(1, 1), a1 + hA, voffA);
;             PG8_WAIT_V(8); PG8_WAIT_L(0); PG8_BAR; PG8_MMA(0, 0, At, B0); PG8_MMA(0, 1, At, B1); PG8_BAR; PG8_SCHED;
;             PG8_LDA(At, 0, 1); PG8_STAGE(PG8_SB(0, 0), b2, voffB); PG8_STAGE(PG8_SB(0, 1), b2 + hB, voffB); PG8_STAGE(PG8_SA(0, 0), a2, voffA);
;             PG8_WAIT_V(8); PG8_WAIT_L(0); PG8_BAR; PG8_MMA(1, 0, At, B0); PG8_MMA(1, 1, At, B1); PG8_BAR; PG8_SCHED;
.LBB0_1154:
	v_add_u32_e32 v144, s90, v200
	v_add_u32_e32 v160, s15, v200
	s_add_u32 s8, s4, s6
	ds_read_b128 v[132:135], v144
	ds_read_b128 v[136:139], v144 offset:1024
	ds_read_b128 v[140:143], v144 offset:2048
	ds_read_b128 v[144:147], v144 offset:3072
	ds_read_b128 v[148:151], v160
	ds_read_b128 v[152:155], v160 offset:1024
	ds_read_b128 v[156:159], v160 offset:2048
	ds_read_b128 v[164:167], v160 offset:3072
	s_addc_u32 s9, s5, s7
	s_add_u32 s8, s8, 0x8000
	s_addc_u32 s9, s9, 0
	s_add_u32 s28, s10, s6
	s_addc_u32 s29, s11, s7
	s_cmp_eq_u32 s6, 0xa8000
	s_cselect_b32 s9, s67, s9
	s_cselect_b32 s8, s66, s8
	s_cselect_b32 vcc_hi, s87, s29
	s_cselect_b32 vcc_lo, s86, s28
	v_lshl_add_u64 v[160:161], v[130:131], 0, s[6:7]
	v_lshl_add_u64 v[196:197], v[160:161], 0, s[76:77]
	s_add_i32 m0, s0, 0xc000
	ds_read_b128 v[168:171], v201
	ds_read_b128 v[172:175], v201 offset:1024
	ds_read_b128 v[176:179], v201 offset:2048
	ds_read_b128 v[180:183], v201 offset:3072
	ds_read_b128 v[184:187], v201 offset:4096
	ds_read_b128 v[188:191], v201 offset:5120
	ds_read_b128 v[192:195], v201 offset:6144
	ds_read_b128 v[212:215], v201 offset:7168
	global_load_lds_dwordx4 v[196:197], off
	v_lshl_add_u64 v[160:161], v[160:161], 0, s[78:79]
	s_add_i32 m0, s0, 0xe000
	s_nop 0
	global_load_lds_dwordx4 v[160:161], off
	s_waitcnt vmcnt(8)
	s_waitcnt lgkmcnt(0)
	s_setprio 1
	s_barrier
	v_mfma_i32_16x16x64_i8 v[122:125], v[132:135], v[168:171], v[122:125]
	v_mfma_i32_16x16x64_i8 v[126:129], v[140:143], v[168:171], v[126:129]
	v_mfma_i32_16x16x64_i8 v[114:117], v[132:135], v[176:179], v[114:117]
	v_mfma_i32_16x16x64_i8 v[118:121], v[140:143], v[176:179], v[118:121]
	v_mfma_i32_16x16x64_i8 v[106:109], v[132:135], v[184:187], v[106:109]
	v_mfma_i32_16x16x64_i8 v[110:113], v[140:143], v[184:187], v[110:113]
	v_mfma_i32_16x16x64_i8 v[98:101], v[132:135], v[192:195], v[98:101]
	v_mfma_i32_16x16x64_i8 v[102:105], v[140:143], v[192:195], v[102:105]
	v_mfma_i32_16x16x64_i8 v[122:125], v[136:139], v[172:175], v[122:125]
	v_mfma_i32_16x16x64_i8 v[126:129], v[144:147], v[172:175], v[126:129]
	v_mfma_i32_16x16x64_i8 v[114:117], v[136:139], v[180:183], v[114:117]
	v_mfma_i32_16x16x64_i8 v[118:121], v[144:147], v[180:183], v[118:121]
	v_mfma_i32_16x16x64_i8 v[106:109], v[136:139], v[188:191], v[106:109]
	v_mfma_i32_16x16x64_i8 v[110:113], v[144:147], v[188:191], v[110:113]
	v_mfma_i32_16x16x64_i8 v[98:101], v[136:139], v[212:215], v[98:101]
	v_mfma_i32_16x16x64_i8 v[102:105], v[144:147], v[212:215], v[102:105]
	v_mfma_i32_16x16x64_i8 v[58:61], v[148:151], v[168:171], v[58:61]
	v_mfma_i32_16x16x64_i8 v[62:65], v[156:159], v[168:171], v[62:65]
	v_mfma_i32_16x16x64_i8 v[50:53], v[148:151], v[176:179], v[50:53]
	v_mfma_i32_16x16x64_i8 v[54:57], v[156:159], v[176:179], v[54:57]
	v_mfma_i32_16x16x64_i8 v[42:45], v[148:151], v[184:187], v[42:45]
	v_mfma_i32_16x16x64_i8 v[46:49], v[156:159], v[184:187], v[46:49]
	v_mfma_i32_16x16x64_i8 v[34:37], v[148:151], v[192:195], v[34:37]
	v_mfma_i32_16x16x64_i8 v[38:41], v[156:159], v[192:195], v[38:41]
	v_mfma_i32_16x16x64_i8 v[58:61], v[152:155], v[172:175], v[58:61]
	v_mfma_i32_16x16x64_i8 v[62:65], v[164:167], v[172:175], v[62:65]
	v_mfma_i32_16x16x64_i8 v[50:53], v[152:155], v[180:183], v[50:53]
	v_mfma_i32_16x16x64_i8 v[54:57], v[164:167], v[180:183], v[54:57]
	v_mfma_i32_16x16x64_i8 v[42:45], v[152:155], v[188:191], v[42:45]
	v_mfma_i32_16x16x64_i8 v[46:49], v[164:167], v[188:191], v[46:49]
	v_mfma_i32_16x16x64_i8 v[34:37], v[152:155], v[212:215], v[34:37]
	v_mfma_i32_16x16x64_i8 v[38:41], v[164:167], v[212:215], v[38:41]
	s_barrier
	s_setprio 0
	s_mov_b32 m0, s91
	v_lshl_add_u64 v[160:161], vcc, 0, v[0:1]
	ds_read_b128 v[168:171], v201 offset:16384
	ds_read_b128 v[172:175], v201 offset:17408
	ds_read_b128 v[176:179], v201 offset:18432
	ds_read_b128 v[180:183], v201 offset:19456
	ds_read_b128 v[184:187], v201 offset:20480
	ds_read_b128 v[188:191], v201 offset:21504
	ds_read_b128 v[192:195], v201 offset:22528
	ds_read_b128 v[212:215], v201 offset:23552
	global_load_lds_dwordx4 v[160:161], off
	v_lshl_add_u64 v[196:197], v[160:161], 0, s[70:71]
	s_mov_b32 m0, s14
	s_nop 0
	global_load_lds_dwordx4 v[196:197], off
	v_lshl_add_u64 v[196:197], v[160:161], 0, s[42:43]
	s_mov_b32 m0, s26
	s_nop 0
	global_load_lds_dwordx4 v[196:197], off
	v_lshl_add_u64 v[196:197], v[160:161], 0, s[48:49]
	s_mov_b32 m0, s27
	s_nop 0
	global_load_lds_dwordx4 v[196:197], off
	v_lshl_add_u64 v[196:197], s[8:9], 0, v[0:1]
	s_mov_b32 m0, s0
	v_lshl_add_u64 v[202:203], v[196:197], 0, s[70:71]
	global_load_lds_dwordx4 v[196:197], off
	s_mov_b32 m0, s1
	s_nop 0
	global_load_lds_dwordx4 v[202:203], off
	s_waitcnt vmcnt(8)
	s_waitcnt lgkmcnt(0)
	s_setprio 1
	s_barrier
; #define PG8_STAGE(bufoff, gbase, unused) do { _Pragma("unroll") for (int _i = 0; _i < 2; ++_i) \
;         __builtin_amdgcn_global_load_lds((const unsigned*)((const char*)(gbase) + voff + _i * 8192), (LAS unsigned*)(lds + (bufoff) + ldsw + _i * 8192), 16, 0, 0); } while (0)
; #define PG8_LDA(dst, b, h) do { _Pragma("unroll") for (int m = 0; m < 4; ++m) _Pragma("unroll") for (int k = 0; k < 2; ++k) dst[m][k] = *(const LAS bf16x8*)(lds + PG8_SA(b, h) + aoff + m * 2048 + (FP8 ? k * 16 : k * 1024)); } while (0)
; #define PG8_LDB(dst, b, h) do { _Pragma("unroll") for (int n = 0; n < 2; ++n) _Pragma("unroll") for (int k = 0; k < 2; ++k) dst[n][k] = *(const LAS bf16x8*)(lds + PG8_SB(b, h) + boff + n * 2048 + (FP8 ? k * 16 : k * 1024)); } while (0)
; #define PG8_WAIT_V(n) asm volatile("s_waitcnt vmcnt(" #n ")" ::: "memory")
; #define PG8_WAIT_L(n) asm volatile("s_waitcnt lgkmcnt(" #n ")" ::: "memory")
; #define PG8_BAR __builtin_amdgcn_s_barrier()
; #define PG8_SCHED __builtin_amdgcn_sched_barrier(0)
; template <class Epi, class Sched, bool ALIGN_EPI, bool SP2, int MODE  >
; __device__ __forceinline__ void gemm_phase(LAS unsigned char* lds, const Gemm g, const Sched S, const Epi E, unsigned long long& probe_acc, int epi_id, int wv) {
;     ...
;             PG8_WAIT_V(8); PG8_WAIT_L(0); PG8_BAR; PG8_MMA(1, 0, At, B0); PG8_MMA(1, 1, At, B1); PG8_BAR; PG8_SCHED;
;             PG8_LDB(B0, 1, 0); PG8_LDB(B1, 1, 1); PG8_SCHED; PG8_LDA(At, 1, 0); PG8_STAGE(PG8_SA(0, 1), a2 + hA, voffA);
;             PG8_WAIT_V(8); PG8_WAIT_L(0); PG8_BAR; PG8_MMA(0, 0, At, B0); PG8_MMA(0, 1, At, B1); PG8_BAR; PG8_SCHED;
	v_mfma_i32_16x16x64_i8 v[90:93], v[132:135], v[168:171], v[90:93]
	v_mfma_i32_16x16x64_i8 v[94:97], v[140:143], v[168:171], v[94:97]
	v_mfma_i32_16x16x64_i8 v[82:85], v[132:135], v[176:179], v[82:85]
	v_mfma_i32_16x16x64_i8 v[86:89], v[140:143], v[176:179], v[86:89]
	v_mfma_i32_16x16x64_i8 v[74:77], v[132:135], v[184:187], v[74:77]
	v_mfma_i32_16x16x64_i8 v[78:81], v[140:143], v[184:187], v[78:81]
	v_mfma_i32_16x16x64_i8 v[66:69], v[132:135], v[192:195], v[66:69]
	v_mfma_i32_16x16x64_i8 v[70:73], v[140:143], v[192:195], v[70:73]
	v_mfma_i32_16x16x64_i8 v[90:93], v[136:139], v[172:175], v[90:93]
	v_mfma_i32_16x16x64_i8 v[94:97], v[144:147], v[172:175], v[94:97]
	v_mfma_i32_16x16x64_i8 v[82:85], v[136:139], v[180:183], v[82:85]
	v_mfma_i32_16x16x64_i8 v[86:89], v[144:147], v[180:183], v[86:89]
	v_mfma_i32_16x16x64_i8 v[74:77], v[136:139], v[188:191], v[74:77]
	v_mfma_i32_16x16x64_i8 v[78:81], v[144:147], v[188:191], v[78:81]
	v_mfma_i32_16x16x64_i8 v[66:69], v[136:139], v[212:215], v[66:69]
	v_mfma_i32_16x16x64_i8 v[70:73], v[144:147], v[212:215], v[70:73]
	v_mfma_i32_16x16x64_i8 v[26:29], v[148:151], v[168:171], v[26:29]
	v_mfma_i32_16x16x64_i8 v[30:33], v[156:159], v[168:171], v[30:33]
	v_mfma_i32_16x16x64_i8 v[18:21], v[148:151], v[176:179], v[18:21]
	v_mfma_i32_16x16x64_i8 v[22:25], v[156:159], v[176:179], v[22:25]
	v_mfma_i32_16x16x64_i8 v[10:13], v[148:151], v[184:187], v[10:13]
	v_mfma_i32_16x16x64_i8 v[14:17], v[156:159], v[184:187], v[14:17]
	v_mfma_i32_16x16x64_i8 v[2:5], v[148:151], v[192:195], v[2:5]
	v_mfma_i32_16x16x64_i8 v[6:9], v[156:159], v[192:195], v[6:9]
	v_mfma_i32_16x16x64_i8 v[26:29], v[152:155], v[172:175], v[26:29]
	v_mfma_i32_16x16x64_i8 v[30:33], v[164:167], v[172:175], v[30:33]
	v_mfma_i32_16x16x64_i8 v[18:21], v[152:155], v[180:183], v[18:21]
	v_mfma_i32_16x16x64_i8 v[22:25], v[164:167], v[180:183], v[22:25]
	v_mfma_i32_16x16x64_i8 v[10:13], v[152:155], v[188:191], v[10:13]
	v_mfma_i32_16x16x64_i8 v[14:17], v[164:167], v[188:191], v[14:17]
	v_mfma_i32_16x16x64_i8 v[2:5], v[152:155], v[212:215], v[2:5]
	v_mfma_i32_16x16x64_i8 v[6:9], v[164:167], v[212:215], v[6:9]
	s_barrier
	s_setprio 0
	v_add_u32_e32 v144, s88, v200
	v_add_u32_e32 v162, s95, v200
	ds_read_b128 v[132:135], v144
	ds_read_b128 v[136:139], v144 offset:1024
	ds_read_b128 v[140:143], v144 offset:2048
	ds_read_b128 v[144:147], v144 offset:3072
	ds_read_b128 v[148:151], v162
	ds_read_b128 v[152:155], v162 offset:1024
	ds_read_b128 v[156:159], v162 offset:2048
	ds_read_b128 v[164:167], v162 offset:3072
	s_add_u32 s8, s8, s40
	s_addc_u32 s9, s9, 0
	s_mov_b32 m0, s36
	v_lshl_add_u64 v[202:203], s[8:9], 0, v[0:1]
	ds_read_b128 v[168:171], v201 offset:32768
	ds_read_b128 v[172:175], v201 offset:33792
	ds_read_b128 v[176:179], v201 offset:34816
	ds_read_b128 v[180:183], v201 offset:35840
	ds_read_b128 v[184:187], v201 offset:36864
	ds_read_b128 v[188:191], v201 offset:37888
	ds_read_b128 v[192:195], v201 offset:38912
	ds_read_b128 v[212:215], v201 offset:39936
	global_load_lds_dwordx4 v[202:203], off
	v_lshl_add_u64 v[202:203], v[202:203], 0, s[70:71]
	s_mov_b32 m0, s37
	s_nop 0
	global_load_lds_dwordx4 v[202:203], off
	s_waitcnt vmcnt(8)
	s_waitcnt lgkmcnt(0)
	s_setprio 1
	s_barrier
	v_mfma_i32_16x16x64_i8 v[122:125], v[132:135], v[168:171], v[122:125]
	v_mfma_i32_16x16x64_i8 v[126:129], v[140:143], v[168:171], v[126:129]
	v_mfma_i32_16x16x64_i8 v[114:117], v[132:135], v[176:179], v[114:117]
	v_mfma_i32_16x16x64_i8 v[118:121], v[140:143], v[176:179], v[118:121]
	v_mfma_i32_16x16x64_i8 v[106:109], v[132:135], v[184:187], v[106:109]
	v_mfma_i32_16x16x64_i8 v[110:113], v[140:143], v[184:187], v[110:113]
	v_mfma_i32_16x16x64_i8 v[98:101], v[132:135], v[192:195], v[98:101]
	v_mfma_i32_16x16x64_i8 v[102:105], v[140:143], v[192:195], v[102:105]
	v_mfma_i32_16x16x64_i8 v[122:125], v[136:139], v[172:175], v[122:125]
	v_mfma_i32_16x16x64_i8 v[126:129], v[144:147], v[172:175], v[126:129]
	v_mfma_i32_16x16x64_i8 v[114:117], v[136:139], v[180:183], v[114:117]
	v_mfma_i32_16x16x64_i8 v[118:121], v[144:147], v[180:183], v[118:121]
	v_mfma_i32_16x16x64_i8 v[106:109], v[136:139], v[188:191], v[106:109]
	v_mfma_i32_16x16x64_i8 v[110:113], v[144:147], v[188:191], v[110:113]
	v_mfma_i32_16x16x64_i8 v[98:101], v[136:139], v[212:215], v[98:101]
	v_mfma_i32_16x16x64_i8 v[102:105], v[144:147], v[212:215], v[102:105]
	v_mfma_i32_16x16x64_i8 v[58:61], v[148:151], v[168:171], v[58:61]
	v_mfma_i32_16x16x64_i8 v[62:65], v[156:159], v[168:171], v[62:65]
	v_mfma_i32_16x16x64_i8 v[50:53], v[148:151], v[176:179], v[50:53]
	v_mfma_i32_16x16x64_i8 v[54:57], v[156:159], v[176:179], v[54:57]
	v_mfma_i32_16x16x64_i8 v[42:45], v[148:151], v[184:187], v[42:45]
	v_mfma_i32_16x16x64_i8 v[46:49], v[156:159], v[184:187], v[46:49]
	v_mfma_i32_16x16x64_i8 v[34:37], v[148:151], v[192:195], v[34:37]
	v_mfma_i32_16x16x64_i8 v[38:41], v[156:159], v[192:195], v[38:41]
	v_mfma_i32_16x16x64_i8 v[58:61], v[152:155], v[172:175], v[58:61]
	v_mfma_i32_16x16x64_i8 v[62:65], v[164:167], v[172:175], v[62:65]
	v_mfma_i32_16x16x64_i8 v[50:53], v[152:155], v[180:183], v[50:53]
	v_mfma_i32_16x16x64_i8 v[54:57], v[164:167], v[180:183], v[54:57]
	v_mfma_i32_16x16x64_i8 v[42:45], v[152:155], v[188:191], v[42:45]
	v_mfma_i32_16x16x64_i8 v[46:49], v[164:167], v[188:191], v[46:49]
	v_mfma_i32_16x16x64_i8 v[34:37], v[152:155], v[212:215], v[34:37]
	v_mfma_i32_16x16x64_i8 v[38:41], v[164:167], v[212:215], v[38:41]
	s_barrier
; #define PG8_STAGE(bufoff, gbase, unused) do { _Pragma("unroll") for (int _i = 0; _i < 2; ++_i) \
;         __builtin_amdgcn_global_load_lds((const unsigned*)((const char*)(gbase) + voff + _i * 8192), (LAS unsigned*)(lds + (bufoff) + ldsw + _i * 8192), 16, 0, 0); } while (0)
; #define PG8_LDA(dst, b, h) do { _Pragma("unroll") for (int m = 0; m < 4; ++m) _Pragma("unroll") for (int k = 0; k < 2; ++k) dst[m][k] = *(const LAS bf16x8*)(lds + PG8_SA(b, h) + aoff + m * 2048 + (FP8 ? k * 16 : k * 1024)); } while (0)
; #define PG8_LDB(dst, b, h) do { _Pragma("unroll") for (int n = 0; n < 2; ++n) _Pragma("unroll") for (int k = 0; k < 2; ++k) dst[n][k] = *(const LAS bf16x8*)(lds + PG8_SB(b, h) + boff + n * 2048 + (FP8 ? k * 16 : k * 1024)); } while (0)
; template <class Epi, class Sched, bool ALIGN_EPI, bool SP2, int MODE  >
; __device__ __forceinline__ void gemm_phase(LAS unsigned char* lds, const Gemm g, const Sched S, const Epi E, unsigned long long& probe_acc, int epi_id, int wv) {
;     ...
;         for (int t = 0; t < nt; t += 2) {
;             const bool last = (t == nt - 2);
;             const char* a1 = cA + (size_t)(t + 1) * kstep;
;             const char* a2 = last ? nA : cA + (size_t)(t + 2) * kstep; const char* b2 = last ? nB : cB + (size_t)(t + 2) * kstep;
;             const char* a3 = a2 + kstep; const char* b3 = b2 + kstep;
;             if constexpr (SP2) {
;             PG8_LDB(B0, 0, 0); PG8_LDB(B1, 0, 1); PG8_SCHED; PG8_LDA(At, 0, 0); PG8_STAGE(PG8_SA(1, 1), a1 + hA, voffA);
;             PG8_WAIT_V(8); PG8_WAIT_L(0); PG8_BAR; PG8_MMA(0, 0, At, B0); PG8_MMA(0, 1, At, B1); PG8_BAR; PG8_SCHED;
;             PG8_LDA(At, 0, 1); PG8_STAGE(PG8_SB(0, 0), b2, voffB); PG8_STAGE(PG8_SB(0, 1), b2 + hB, voffB); PG8_STAGE(PG8_SA(0, 0), a2, voffA);
;             PG8_WAIT_V(8); PG8_WAIT_L(0); PG8_BAR; PG8_MMA(1, 0, At, B0); PG8_MMA(1, 1, At, B1); PG8_BAR; PG8_SCHED;
;             PG8_LDB(B0, 1, 0); PG8_LDB(B1, 1, 1); PG8_SCHED; PG8_LDA(At, 1, 0); PG8_STAGE(PG8_SA(0, 1), a2 + hA, voffA);
;             PG8_WAIT_V(8); PG8_WAIT_L(0); PG8_BAR; PG8_MMA(0, 0, At, B0); PG8_MMA(0, 1, At, B1); PG8_BAR; PG8_SCHED;
;             PG8_LDA(At, 1, 1); PG8_STAGE(PG8_SB(1, 0), b3, voffB); PG8_STAGE(PG8_SB(1, 1), b3 + hB, voffB); PG8_STAGE(PG8_SA(1, 0), a3, voffA);
;             PG8_WAIT_V(8); PG8_WAIT_L(0); PG8_BAR; PG8_MMA(1, 0, At, B0); PG8_MMA(1, 1, At, B1); PG8_BAR; PG8_SCHED;
	s_setprio 0
	s_mov_b32 m0, s89
	v_lshl_add_u64 v[202:203], v[160:161], 0, s[76:77]
	ds_read_b128 v[168:171], v201 offset:49152
	ds_read_b128 v[172:175], v201 offset:50176
	ds_read_b128 v[176:179], v201 offset:51200
	ds_read_b128 v[180:183], v201 offset:52224
	ds_read_b128 v[184:187], v201 offset:53248
	ds_read_b128 v[188:191], v201 offset:54272
	ds_read_b128 v[192:195], v201 offset:55296
	ds_read_b128 v[212:215], v201 offset:56320
	global_load_lds_dwordx4 v[202:203], off
	v_lshl_add_u64 v[202:203], v[160:161], 0, s[78:79]
	s_mov_b32 m0, s92
	s_nop 0
	global_load_lds_dwordx4 v[202:203], off
	v_lshl_add_u64 v[202:203], v[160:161], 0, s[44:45]
	s_mov_b32 m0, s84
	v_lshl_add_u64 v[160:161], v[160:161], 0, s[56:57]
	global_load_lds_dwordx4 v[202:203], off
	s_mov_b32 m0, s12
	s_nop 0
	global_load_lds_dwordx4 v[160:161], off
	v_lshl_add_u64 v[160:161], v[196:197], 0, s[76:77]
	s_mov_b32 m0, s93
	s_nop 0
	global_load_lds_dwordx4 v[160:161], off
	v_lshl_add_u64 v[160:161], v[196:197], 0, s[78:79]
	s_mov_b32 m0, s94
	s_nop 0
	global_load_lds_dwordx4 v[160:161], off
	s_add_i32 s34, s34, 2
	s_add_u32 s6, s6, 0x8000
	s_addc_u32 s7, s7, 0
	s_waitcnt vmcnt(8)
	s_waitcnt lgkmcnt(0)
	s_setprio 1
	s_barrier
	v_mfma_i32_16x16x64_i8 v[90:93], v[132:135], v[168:171], v[90:93]
	v_mfma_i32_16x16x64_i8 v[94:97], v[140:143], v[168:171], v[94:97]
	v_mfma_i32_16x16x64_i8 v[82:85], v[132:135], v[176:179], v[82:85]
	v_mfma_i32_16x16x64_i8 v[86:89], v[140:143], v[176:179], v[86:89]
	v_mfma_i32_16x16x64_i8 v[74:77], v[132:135], v[184:187], v[74:77]
	v_mfma_i32_16x16x64_i8 v[78:81], v[140:143], v[184:187], v[78:81]
	v_mfma_i32_16x16x64_i8 v[66:69], v[132:135], v[192:195], v[66:69]
	v_mfma_i32_16x16x64_i8 v[70:73], v[140:143], v[192:195], v[70:73]
	v_mfma_i32_16x16x64_i8 v[90:93], v[136:139], v[172:175], v[90:93]
	v_mfma_i32_16x16x64_i8 v[94:97], v[144:147], v[172:175], v[94:97]
	v_mfma_i32_16x16x64_i8 v[82:85], v[136:139], v[180:183], v[82:85]
	v_mfma_i32_16x16x64_i8 v[86:89], v[144:147], v[180:183], v[86:89]
	v_mfma_i32_16x16x64_i8 v[74:77], v[136:139], v[188:191], v[74:77]
	v_mfma_i32_16x16x64_i8 v[78:81], v[144:147], v[188:191], v[78:81]
	v_mfma_i32_16x16x64_i8 v[66:69], v[136:139], v[212:215], v[66:69]
	v_mfma_i32_16x16x64_i8 v[70:73], v[144:147], v[212:215], v[70:73]
	v_mfma_i32_16x16x64_i8 v[26:29], v[148:151], v[168:171], v[26:29]
	v_mfma_i32_16x16x64_i8 v[30:33], v[156:159], v[168:171], v[30:33]
	v_mfma_i32_16x16x64_i8 v[18:21], v[148:151], v[176:179], v[18:21]
	v_mfma_i32_16x16x64_i8 v[22:25], v[156:159], v[176:179], v[22:25]
	v_mfma_i32_16x16x64_i8 v[10:13], v[148:151], v[184:187], v[10:13]
	v_mfma_i32_16x16x64_i8 v[14:17], v[156:159], v[184:187], v[14:17]
	v_mfma_i32_16x16x64_i8 v[2:5], v[148:151], v[192:195], v[2:5]
	v_mfma_i32_16x16x64_i8 v[6:9], v[156:159], v[192:195], v[6:9]
	v_mfma_i32_16x16x64_i8 v[26:29], v[152:155], v[172:175], v[26:29]
	v_mfma_i32_16x16x64_i8 v[30:33], v[164:167], v[172:175], v[30:33]
	v_mfma_i32_16x16x64_i8 v[18:21], v[152:155], v[180:183], v[18:21]
	v_mfma_i32_16x16x64_i8 v[22:25], v[164:167], v[180:183], v[22:25]
	v_mfma_i32_16x16x64_i8 v[10:13], v[152:155], v[188:191], v[10:13]
	v_mfma_i32_16x16x64_i8 v[14:17], v[164:167], v[188:191], v[14:17]
	v_mfma_i32_16x16x64_i8 v[2:5], v[152:155], v[212:215], v[2:5]
	v_mfma_i32_16x16x64_i8 v[6:9], v[164:167], v[212:215], v[6:9]
	s_barrier
	s_setprio 0
	s_cmp_gt_u32 s34, 41
	s_cbranch_scc0 .LBB0_1154
	v_readlane_b32 s4, v255, 34
	v_readlane_b32 s5, v255, 35
	s_and_b64 vcc, exec, s[4:5]
	s_cbranch_vccz .LBB0_1157
	s_barrier
